# up-GEMM conv epilogue: dead zero-inits of row_ror DPP moves removed (hazards re-padded)
# speedup vs baseline: 1.0665x; 1.0059x over previous
.LBB0_57:
	v_readlane_b32 s4, v238, 9
	s_lshl_b32 s3, s3, 7
	s_mov_b64 s[52:53], s[80:81]
	v_add_u32_e32 v212, s4, v130
	v_readlane_b32 s4, v239, 62
	s_or_b32 s3, s3, s4
	v_lshl_add_u32 v174, v129, 3, s3
	s_lshl_b32 s3, s6, 8
	v_readlane_b32 s4, v239, 60
	s_add_i32 s3, s3, s4
	v_add_u32_e32 v130, s3, v128
	v_mov_b64_e32 v[128:129], s[90:91]
	s_movk_i32 s3, 0x1600
	v_mad_i64_i32 v[128:129], s[4:5], v130, s3, v[128:129]
	v_ashrrev_i32_e32 v175, 31, v174
	v_lshl_add_u64 v[172:173], v[174:175], 1, v[128:129]
	v_lshlrev_b64 v[128:129], 2, v[174:175]
	v_readlane_b32 s4, v238, 0
	v_lshl_add_u64 v[178:179], s[76:77], 0, v[128:129]
	v_readlane_b32 s5, v238, 1
	s_movk_i32 s3, 0x2000
	v_lshl_add_u64 v[140:141], s[52:53], 0, v[128:129]
	v_lshl_add_u64 v[182:183], s[4:5], 0, v[128:129]
	v_add_co_u32_e64 v184, s[4:5], s3, v178
	s_mov_b64 s[68:69], s[86:87]
	s_nop 0
	v_addc_co_u32_e64 v185, s[4:5], 0, v179, s[4:5]
	v_add_co_u32_e64 v186, s[4:5], s3, v140
	v_lshl_add_u64 v[152:153], s[68:69], 0, v[128:129]
	s_nop 0
	v_addc_co_u32_e64 v187, s[4:5], 0, v141, s[4:5]
	v_add_co_u32_e64 v176, s[4:5], s3, v152
	global_load_dwordx4 v[144:147], v[140:141], off
	global_load_dwordx4 v[148:151], v[152:153], off
	v_addc_co_u32_e64 v177, s[4:5], 0, v153, s[4:5]
	v_add_co_u32_e64 v180, s[4:5], s3, v182
	global_load_dwordx4 v[128:131], v[182:183], off
	s_nop 0
	v_addc_co_u32_e64 v181, s[4:5], 0, v183, s[4:5]
	global_load_dwordx4 v[132:135], v[178:179], off
	global_load_dwordx4 v[152:155], v[176:177], off offset:3072
	global_load_dwordx4 v[156:159], v[180:181], off offset:3072
	global_load_dwordx4 v[136:139], v[184:185], off offset:3072
	global_load_dwordx4 v[140:143], v[186:187], off offset:3072
	v_add_u32_e32 v175, 0xffffff00, v212
	ds_read_b128 v[214:217], v175
	v_add_u32_e32 v175, 0xffffff80, v212
	ds_read_b128 v[224:227], v175
	ds_read_b128 v[228:231], v212
	ds_read_b128 v[232:235], v212 offset:128
	s_and_b64 s[6:7], s[88:89], vcc
	s_mov_b32 s3, 0x16000
	s_waitcnt lgkmcnt(0)
	v_cndmask_b32_e64 v223, 0, v226, s[6:7]
	v_cndmask_b32_e64 v221, 0, v227, s[6:7]
	v_mov_b32_dpp v226, v116 row_ror:15 row_mask:0xf bank_mask:0xf
	v_cndmask_b32_e64 v237, 0, v214, s[6:7]
	v_mov_b32_dpp v227, v112 row_ror:15 row_mask:0xf bank_mask:0xf
	v_mov_b32_dpp v226, v124 row_shl:1 row_mask:0xf bank_mask:0xf
	v_cndmask_b32_e64 v224, 0, v224, s[6:7]
	v_mov_b32_dpp v227, v120 row_shl:1 row_mask:0xf bank_mask:0xf
	v_mov_b32_dpp v237, v124 row_shr:1 row_mask:0xf bank_mask:0xf
	v_mov_b32_dpp v224, v120 row_shr:1 row_mask:0xf bank_mask:0xf
	v_cndmask_b32_e64 v236, 0, v215, s[6:7]
	v_cndmask_b32_e64 v225, 0, v225, s[6:7]
	v_cndmask_b32_e64 v222, 0, v216, s[6:7]
	v_mov_b32_dpp v236, v125 row_shr:1 row_mask:0xf bank_mask:0xf
	v_mov_b32_dpp v225, v121 row_shr:1 row_mask:0xf bank_mask:0xf
	v_mov_b32_dpp v222, v126 row_shr:1 row_mask:0xf bank_mask:0xf
	v_mov_b32_dpp v223, v122 row_shr:1 row_mask:0xf bank_mask:0xf
	v_cndmask_b32_e64 v220, 0, v217, s[6:7]
	v_mov_b32_dpp v221, v123 row_shr:1 row_mask:0xf bank_mask:0xf
	v_cndmask_b32_e32 v219, 0, v228, vcc
	v_mov_b32_dpp v220, v127 row_shr:1 row_mask:0xf bank_mask:0xf
	v_cndmask_b32_e32 v218, 0, v232, vcc
	v_mov_b32_dpp v219, v100 row_shl:1 row_mask:0xf bank_mask:0xf
	v_cndmask_b32_e32 v217, 0, v229, vcc
	v_mov_b32_dpp v218, v96 row_shl:1 row_mask:0xf bank_mask:0xf
	v_cndmask_b32_e32 v216, 0, v233, vcc
	v_mov_b32_dpp v217, v101 row_shl:1 row_mask:0xf bank_mask:0xf
	v_cndmask_b32_e32 v215, 0, v230, vcc
	v_mov_b32_dpp v216, v97 row_shl:1 row_mask:0xf bank_mask:0xf
	v_cndmask_b32_e32 v214, 0, v234, vcc
	v_mov_b32_dpp v215, v102 row_shl:1 row_mask:0xf bank_mask:0xf
	v_cndmask_b32_e32 v213, 0, v231, vcc
	v_mov_b32_dpp v214, v98 row_shl:1 row_mask:0xf bank_mask:0xf
	v_cndmask_b32_e32 v175, 0, v235, vcc
	v_mov_b32_dpp v213, v103 row_shl:1 row_mask:0xf bank_mask:0xf
	s_waitcnt vmcnt(0)
	v_fma_f32 v226, v148, v226, v128
	v_fmac_f32_e32 v226, v144, v124
	v_mov_b32_dpp v175, v99 row_shl:1 row_mask:0xf bank_mask:0xf
	v_fmac_f32_e32 v226, v132, v237
	v_fma_f32 v227, v152, v227, v156
	v_fmac_f32_e32 v227, v140, v120
	v_fmac_f32_e32 v227, v136, v224
	v_mul_f32_e32 v224, 0xbfb8aa3b, v226
	v_exp_f32_e32 v224, v224
	s_nop 0
	v_add_f32_e32 v224, 1.0, v224
	v_rcp_f32_e32 v224, v224
	s_nop 0
	v_mul_f32_e32 v224, v226, v224
	v_mul_f32_e32 v224, v227, v224
	v_mov_b32_dpp v226, v117 row_ror:15 row_mask:0xf bank_mask:0xf
	s_nop 0
	v_mov_b32_dpp v227, v113 row_ror:15 row_mask:0xf bank_mask:0xf
	v_mov_b32_dpp v226, v125 row_shl:1 row_mask:0xf bank_mask:0xf
	v_fma_f32 v226, v149, v226, v129
	v_mov_b32_dpp v227, v121 row_shl:1 row_mask:0xf bank_mask:0xf
	v_fmac_f32_e32 v226, v145, v125
	v_fma_f32 v227, v153, v227, v157
	v_fmac_f32_e32 v226, v133, v236
	v_fmac_f32_e32 v227, v141, v121
	v_fmac_f32_e32 v227, v137, v225
	v_mul_f32_e32 v225, 0xbfb8aa3b, v226
	v_exp_f32_e32 v225, v225
	s_nop 0
	v_add_f32_e32 v225, 1.0, v225
	v_rcp_f32_e32 v225, v225
	s_nop 0
	v_mul_f32_e32 v225, v226, v225
	v_mul_f32_e32 v225, v227, v225
	v_mov_b32_dpp v226, v118 row_ror:15 row_mask:0xf bank_mask:0xf
	s_nop 0
	v_mov_b32_dpp v227, v114 row_ror:15 row_mask:0xf bank_mask:0xf
	v_mov_b32_dpp v226, v126 row_shl:1 row_mask:0xf bank_mask:0xf
	v_fma_f32 v226, v150, v226, v130
	v_mov_b32_dpp v227, v122 row_shl:1 row_mask:0xf bank_mask:0xf
	v_fmac_f32_e32 v226, v146, v126
	v_fmac_f32_e32 v226, v134, v222
	v_fma_f32 v222, v154, v227, v158
	v_fmac_f32_e32 v222, v142, v122
	v_fmac_f32_e32 v222, v138, v223
	v_mul_f32_e32 v223, 0xbfb8aa3b, v226
	v_exp_f32_e32 v223, v223
	s_nop 0
	v_add_f32_e32 v223, 1.0, v223
	v_rcp_f32_e32 v223, v223
	s_nop 0
	v_mul_f32_e32 v223, v226, v223
	v_mul_f32_e32 v222, v222, v223
	s_nop 0
	v_mov_b32_dpp v223, v119 row_ror:15 row_mask:0xf bank_mask:0xf
	v_mov_b32_dpp v226, v115 row_ror:15 row_mask:0xf bank_mask:0xf
	s_nop 0
	v_mov_b32_dpp v223, v127 row_shl:1 row_mask:0xf bank_mask:0xf
	v_fma_f32 v223, v151, v223, v131
	v_mov_b32_dpp v226, v123 row_shl:1 row_mask:0xf bank_mask:0xf
	v_fmac_f32_e32 v223, v147, v127
	v_fmac_f32_e32 v223, v135, v220
	v_fma_f32 v220, v155, v226, v159
	v_fmac_f32_e32 v220, v143, v123
	v_fmac_f32_e32 v220, v139, v221
	v_mul_f32_e32 v221, 0xbfb8aa3b, v223
	v_exp_f32_e32 v221, v221
	s_nop 0
	v_add_f32_e32 v221, 1.0, v221
	v_rcp_f32_e32 v221, v221
	s_nop 0
	v_mul_f32_e32 v221, v223, v221
	v_mul_f32_e32 v221, v220, v221
	v_cvt_pk_bf16_f32 v220, v224, v225
	v_cvt_pk_bf16_f32 v221, v222, v221
	flat_store_dwordx2 v[172:173], v[220:221]
	s_nop 0
	v_mov_b32_dpp v220, v124 row_ror:1 row_mask:0xf bank_mask:0xf
	v_mov_b32_dpp v221, v104 row_ror:15 row_mask:0xf bank_mask:0xf
	s_nop 0
	v_mov_b32_dpp v220, v116 row_shr:1 row_mask:0xf bank_mask:0xf
	v_mov_b32_dpp v124, v120 row_ror:1 row_mask:0xf bank_mask:0xf
	v_mov_b32_dpp v221, v112 row_shl:1 row_mask:0xf bank_mask:0xf
	s_nop 0
	v_mov_b32_dpp v124, v112 row_shr:1 row_mask:0xf bank_mask:0xf
	v_mov_b32_dpp v120, v108 row_ror:15 row_mask:0xf bank_mask:0xf
	s_nop 1
	v_mov_b32_dpp v120, v116 row_shl:1 row_mask:0xf bank_mask:0xf
	v_fma_f32 v120, v148, v120, v128
	v_fmac_f32_e32 v120, v144, v116
	v_fmac_f32_e32 v120, v132, v220
	v_fma_f32 v220, v152, v221, v156
	v_fmac_f32_e32 v220, v140, v112
	v_fmac_f32_e32 v220, v136, v124
	v_mul_f32_e32 v124, 0xbfb8aa3b, v120
	v_exp_f32_e32 v124, v124
	s_nop 0
	v_add_f32_e32 v124, 1.0, v124
	v_rcp_f32_e32 v124, v124
	s_nop 0
	v_mul_f32_e32 v120, v120, v124
	v_mul_f32_e32 v120, v220, v120
	v_mov_b32_dpp v124, v125 row_ror:1 row_mask:0xf bank_mask:0xf
	v_mov_b32_dpp v220, v105 row_ror:15 row_mask:0xf bank_mask:0xf
	s_nop 0
	v_mov_b32_dpp v124, v117 row_shr:1 row_mask:0xf bank_mask:0xf
	v_mov_b32_dpp v125, v121 row_ror:1 row_mask:0xf bank_mask:0xf
	v_mov_b32_dpp v220, v113 row_shl:1 row_mask:0xf bank_mask:0xf
	s_nop 0
	v_mov_b32_dpp v125, v113 row_shr:1 row_mask:0xf bank_mask:0xf
	v_mov_b32_dpp v121, v109 row_ror:15 row_mask:0xf bank_mask:0xf
	s_nop 1
	v_mov_b32_dpp v121, v117 row_shl:1 row_mask:0xf bank_mask:0xf
	v_fma_f32 v121, v149, v121, v129
	v_fmac_f32_e32 v121, v145, v117
	v_fmac_f32_e32 v121, v133, v124
	v_fma_f32 v124, v153, v220, v157
	v_fmac_f32_e32 v124, v141, v113
	v_fmac_f32_e32 v124, v137, v125
	v_mul_f32_e32 v125, 0xbfb8aa3b, v121
	v_exp_f32_e32 v125, v125
	s_nop 0
	v_add_f32_e32 v125, 1.0, v125
	v_rcp_f32_e32 v125, v125
	s_nop 0
	v_mul_f32_e32 v121, v121, v125
	v_mul_f32_e32 v121, v124, v121
	v_mov_b32_dpp v125, v122 row_ror:1 row_mask:0xf bank_mask:0xf
	v_mov_b32_dpp v124, v126 row_ror:1 row_mask:0xf bank_mask:0xf
	v_mov_b32_dpp v122, v110 row_ror:15 row_mask:0xf bank_mask:0xf
	s_nop 0
	v_mov_b32_dpp v124, v118 row_shr:1 row_mask:0xf bank_mask:0xf
	v_mov_b32_dpp v126, v106 row_ror:15 row_mask:0xf bank_mask:0xf
	v_mov_b32_dpp v122, v118 row_shl:1 row_mask:0xf bank_mask:0xf
	v_fma_f32 v122, v150, v122, v130
	v_mov_b32_dpp v126, v114 row_shl:1 row_mask:0xf bank_mask:0xf
	v_fmac_f32_e32 v122, v146, v118
	v_fmac_f32_e32 v122, v134, v124
	v_fma_f32 v124, v154, v126, v158
	v_mov_b32_dpp v125, v114 row_shr:1 row_mask:0xf bank_mask:0xf
	v_fmac_f32_e32 v124, v142, v114
	v_fmac_f32_e32 v124, v138, v125
	v_mul_f32_e32 v125, 0xbfb8aa3b, v122
	v_exp_f32_e32 v125, v125
	s_nop 0
	v_add_f32_e32 v125, 1.0, v125
	v_rcp_f32_e32 v125, v125
	v_mov_b32_dpp v126, v107 row_ror:15 row_mask:0xf bank_mask:0xf
	v_mul_f32_e32 v122, v122, v125
	v_mul_f32_e32 v124, v124, v122
	v_mov_b32_dpp v125, v123 row_ror:1 row_mask:0xf bank_mask:0xf
	v_mov_b32_dpp v122, v127 row_ror:1 row_mask:0xf bank_mask:0xf
	v_mov_b32_dpp v126, v115 row_shl:1 row_mask:0xf bank_mask:0xf
	v_mov_b32_dpp v123, v111 row_ror:15 row_mask:0xf bank_mask:0xf
	v_mov_b32_dpp v122, v119 row_shr:1 row_mask:0xf bank_mask:0xf
	v_mov_b32_dpp v125, v115 row_shr:1 row_mask:0xf bank_mask:0xf
	v_mov_b32_dpp v123, v119 row_shl:1 row_mask:0xf bank_mask:0xf
	v_fma_f32 v123, v151, v123, v131
	v_fmac_f32_e32 v123, v147, v119
	v_fmac_f32_e32 v123, v135, v122
	v_fma_f32 v122, v155, v126, v159
	v_fmac_f32_e32 v122, v143, v115
	v_fmac_f32_e32 v122, v139, v125
	v_mul_f32_e32 v125, 0xbfb8aa3b, v123
	v_exp_f32_e32 v125, v125
	s_nop 0
	v_add_f32_e32 v125, 1.0, v125
	v_rcp_f32_e32 v125, v125
	s_nop 0
	v_mul_f32_e32 v123, v123, v125
	v_mul_f32_e32 v123, v122, v123
	v_cvt_pk_bf16_f32 v122, v120, v121
	v_add_co_u32_e64 v120, s[4:5], s3, v172
	v_cvt_pk_bf16_f32 v123, v124, v123
	s_mov_b32 s3, 0x2c000
	s_nop 0
	v_addc_co_u32_e64 v121, s[4:5], 0, v173, s[4:5]
	flat_store_dwordx2 v[120:121], v[122:123]
	s_nop 0
	v_mov_b32_dpp v122, v116 row_ror:1 row_mask:0xf bank_mask:0xf
	v_mov_b32_dpp v123, v96 row_ror:15 row_mask:0xf bank_mask:0xf
	s_nop 0
	v_mov_b32_dpp v122, v108 row_shr:1 row_mask:0xf bank_mask:0xf
	v_mov_b32_dpp v116, v112 row_ror:1 row_mask:0xf bank_mask:0xf
	v_mov_b32_dpp v123, v104 row_shl:1 row_mask:0xf bank_mask:0xf
	s_nop 0
	v_mov_b32_dpp v116, v104 row_shr:1 row_mask:0xf bank_mask:0xf
	v_mov_b32_dpp v112, v100 row_ror:15 row_mask:0xf bank_mask:0xf
	s_nop 1
	v_mov_b32_dpp v112, v108 row_shl:1 row_mask:0xf bank_mask:0xf
	v_fma_f32 v112, v148, v112, v128
	v_fmac_f32_e32 v112, v144, v108
	v_fmac_f32_e32 v112, v132, v122
	v_fma_f32 v122, v152, v123, v156
	v_fmac_f32_e32 v122, v140, v104
	v_fmac_f32_e32 v122, v136, v116
	v_mul_f32_e32 v116, 0xbfb8aa3b, v112
	v_exp_f32_e32 v116, v116
	s_nop 0
	v_add_f32_e32 v116, 1.0, v116
	v_rcp_f32_e32 v116, v116
	s_nop 0
	v_mul_f32_e32 v112, v112, v116
	v_mul_f32_e32 v112, v122, v112
	v_mov_b32_dpp v116, v117 row_ror:1 row_mask:0xf bank_mask:0xf
	v_mov_b32_dpp v122, v97 row_ror:15 row_mask:0xf bank_mask:0xf
	s_nop 0
	v_mov_b32_dpp v116, v109 row_shr:1 row_mask:0xf bank_mask:0xf
	v_mov_b32_dpp v117, v113 row_ror:1 row_mask:0xf bank_mask:0xf
	v_mov_b32_dpp v122, v105 row_shl:1 row_mask:0xf bank_mask:0xf
	s_nop 0
	v_mov_b32_dpp v117, v105 row_shr:1 row_mask:0xf bank_mask:0xf
	v_mov_b32_dpp v113, v101 row_ror:15 row_mask:0xf bank_mask:0xf
	s_nop 1
	v_mov_b32_dpp v113, v109 row_shl:1 row_mask:0xf bank_mask:0xf
	v_fma_f32 v113, v149, v113, v129
	v_fmac_f32_e32 v113, v145, v109
	v_fmac_f32_e32 v113, v133, v116
	v_fma_f32 v116, v153, v122, v157
	v_fmac_f32_e32 v116, v141, v105
	v_fmac_f32_e32 v116, v137, v117
	v_mul_f32_e32 v117, 0xbfb8aa3b, v113
	v_exp_f32_e32 v117, v117
	s_nop 0
	v_add_f32_e32 v117, 1.0, v117
	v_rcp_f32_e32 v117, v117
	s_nop 0
	v_mul_f32_e32 v113, v113, v117
	v_mul_f32_e32 v113, v116, v113
	v_mov_b32_dpp v117, v114 row_ror:1 row_mask:0xf bank_mask:0xf
	v_mov_b32_dpp v116, v118 row_ror:1 row_mask:0xf bank_mask:0xf
	v_mov_b32_dpp v114, v102 row_ror:15 row_mask:0xf bank_mask:0xf
	s_nop 0
	v_mov_b32_dpp v116, v110 row_shr:1 row_mask:0xf bank_mask:0xf
	v_mov_b32_dpp v118, v98 row_ror:15 row_mask:0xf bank_mask:0xf
	v_mov_b32_dpp v114, v110 row_shl:1 row_mask:0xf bank_mask:0xf
	v_fma_f32 v114, v150, v114, v130
	v_mov_b32_dpp v118, v106 row_shl:1 row_mask:0xf bank_mask:0xf
	v_fmac_f32_e32 v114, v146, v110
	v_fmac_f32_e32 v114, v134, v116
	v_fma_f32 v116, v154, v118, v158
	v_mov_b32_dpp v117, v106 row_shr:1 row_mask:0xf bank_mask:0xf
	v_fmac_f32_e32 v116, v142, v106
	v_fmac_f32_e32 v116, v138, v117
	v_mul_f32_e32 v117, 0xbfb8aa3b, v114
	v_exp_f32_e32 v117, v117
	s_nop 0
	v_add_f32_e32 v117, 1.0, v117
	v_rcp_f32_e32 v117, v117
	v_mov_b32_dpp v118, v99 row_ror:15 row_mask:0xf bank_mask:0xf
	v_mul_f32_e32 v114, v114, v117
	v_mul_f32_e32 v116, v116, v114
	v_mov_b32_dpp v117, v115 row_ror:1 row_mask:0xf bank_mask:0xf
	v_mov_b32_dpp v114, v119 row_ror:1 row_mask:0xf bank_mask:0xf
	v_mov_b32_dpp v118, v107 row_shl:1 row_mask:0xf bank_mask:0xf
	v_mov_b32_dpp v115, v103 row_ror:15 row_mask:0xf bank_mask:0xf
	v_mov_b32_dpp v114, v111 row_shr:1 row_mask:0xf bank_mask:0xf
	v_mov_b32_dpp v117, v107 row_shr:1 row_mask:0xf bank_mask:0xf
	v_mov_b32_dpp v115, v111 row_shl:1 row_mask:0xf bank_mask:0xf
	v_fma_f32 v115, v151, v115, v131
	v_fmac_f32_e32 v115, v147, v111
	v_fmac_f32_e32 v115, v135, v114
	v_fma_f32 v114, v155, v118, v159
	v_fmac_f32_e32 v114, v143, v107
	v_fmac_f32_e32 v114, v139, v117
	v_mul_f32_e32 v117, 0xbfb8aa3b, v115
	v_exp_f32_e32 v117, v117
	s_nop 0
	v_add_f32_e32 v117, 1.0, v117
	v_rcp_f32_e32 v117, v117
	s_nop 0
	v_mul_f32_e32 v115, v115, v117
	v_mul_f32_e32 v115, v114, v115
	v_cvt_pk_bf16_f32 v114, v112, v113
	v_add_co_u32_e64 v112, s[4:5], s3, v172
	v_cvt_pk_bf16_f32 v115, v116, v115
	s_nop 1
	v_addc_co_u32_e64 v113, s[4:5], 0, v173, s[4:5]
	flat_store_dwordx2 v[112:113], v[114:115]
	s_nop 1
	v_mov_b32_dpp v114, v108 row_ror:1 row_mask:0xf bank_mask:0xf
	s_nop 0
	s_nop 0
	v_mov_b32_dpp v114, v100 row_shr:1 row_mask:0xf bank_mask:0xf
	v_mov_b32_dpp v108, v104 row_ror:1 row_mask:0xf bank_mask:0xf
	v_fma_f32 v104, v148, v219, v128
	v_fmac_f32_e32 v104, v144, v100
	v_fmac_f32_e32 v104, v132, v114
	v_fma_f32 v100, v152, v218, v156
	v_mov_b32_dpp v108, v96 row_shr:1 row_mask:0xf bank_mask:0xf
	v_fmac_f32_e32 v100, v140, v96
	v_mul_f32_e32 v96, 0xbfb8aa3b, v104
	v_exp_f32_e32 v96, v96
	v_fmac_f32_e32 v100, v136, v108
	v_add_f32_e32 v96, 1.0, v96
	v_rcp_f32_e32 v96, v96
	s_nop 0
	v_mul_f32_e32 v96, v104, v96
	v_mul_f32_e32 v96, v100, v96
	s_nop 0
	v_mov_b32_dpp v100, v109 row_ror:1 row_mask:0xf bank_mask:0xf
	v_mov_b32_dpp v104, v105 row_ror:1 row_mask:0xf bank_mask:0xf
	v_fma_f32 v105, v149, v217, v129
	v_mov_b32_dpp v100, v101 row_shr:1 row_mask:0xf bank_mask:0xf
	v_fmac_f32_e32 v105, v145, v101
	v_fmac_f32_e32 v105, v133, v100
	v_fma_f32 v100, v153, v216, v157
	v_mov_b32_dpp v104, v97 row_shr:1 row_mask:0xf bank_mask:0xf
	v_fmac_f32_e32 v100, v141, v97
	v_mul_f32_e32 v97, 0xbfb8aa3b, v105
	v_exp_f32_e32 v97, v97
	v_fmac_f32_e32 v100, v137, v104
	v_fma_f32 v104, v150, v215, v130
	v_add_f32_e32 v97, 1.0, v97
	v_rcp_f32_e32 v97, v97
	v_fmac_f32_e32 v104, v146, v102
	v_mov_b32_dpp v101, v106 row_ror:1 row_mask:0xf bank_mask:0xf
	v_mul_f32_e32 v97, v105, v97
	v_mul_f32_e32 v97, v100, v97
	v_mov_b32_dpp v101, v98 row_shr:1 row_mask:0xf bank_mask:0xf
	s_nop 0
	v_mov_b32_dpp v100, v110 row_ror:1 row_mask:0xf bank_mask:0xf
	s_nop 1
	v_mov_b32_dpp v100, v102 row_shr:1 row_mask:0xf bank_mask:0xf
	v_fmac_f32_e32 v104, v134, v100
	v_fma_f32 v100, v154, v214, v158
	v_fmac_f32_e32 v100, v142, v98
	v_mul_f32_e32 v98, 0xbfb8aa3b, v104
	v_exp_f32_e32 v98, v98
	v_fmac_f32_e32 v100, v138, v101
	v_fma_f32 v102, v151, v213, v131
	v_add_f32_e32 v98, 1.0, v98
	v_rcp_f32_e32 v98, v98
	v_fmac_f32_e32 v102, v147, v103
	v_mov_b32_dpp v101, v107 row_ror:1 row_mask:0xf bank_mask:0xf
	v_mul_f32_e32 v98, v104, v98
	v_mul_f32_e32 v100, v100, v98
	v_mov_b32_dpp v101, v99 row_shr:1 row_mask:0xf bank_mask:0xf
	s_nop 0
	v_mov_b32_dpp v98, v111 row_ror:1 row_mask:0xf bank_mask:0xf
	s_nop 1
	v_mov_b32_dpp v98, v103 row_shr:1 row_mask:0xf bank_mask:0xf
	v_fmac_f32_e32 v102, v135, v98
	v_fma_f32 v98, v155, v175, v159
	v_fmac_f32_e32 v98, v143, v99
	v_mul_f32_e32 v99, 0xbfb8aa3b, v102
	v_exp_f32_e32 v99, v99
	v_fmac_f32_e32 v98, v139, v101
	v_add_f32_e32 v99, 1.0, v99
	v_rcp_f32_e32 v99, v99
	s_nop 0
	v_mul_f32_e32 v99, v102, v99
	v_mul_f32_e32 v99, v98, v99
	v_cvt_pk_bf16_f32 v98, v96, v97
	v_add_co_u32_e64 v96, s[4:5], s63, v172
	v_cvt_pk_bf16_f32 v99, v100, v99
	s_nop 1
	v_addc_co_u32_e64 v97, s[4:5], 0, v173, s[4:5]
	flat_store_dwordx2 v[96:97], v[98:99]
	ds_read_b128 v[98:101], v212 offset:256
	ds_read_b128 v[102:105], v212 offset:384
	ds_read_b128 v[108:111], v212 offset:512
	ds_read_b128 v[114:117], v212 offset:640
	s_and_b64 s[4:5], s[54:55], vcc
	s_waitcnt lgkmcnt(0)
	v_cndmask_b32_e32 v99, 0, v99, vcc
	v_cndmask_b32_e32 v102, 0, v102, vcc
	v_cndmask_b32_e64 v107, 0, v110, s[4:5]
	v_cndmask_b32_e64 v110, 0, v108, s[4:5]
	v_cndmask_b32_e64 v108, 0, v115, s[4:5]
	v_mov_b32_dpp v102, v88 row_shr:1 row_mask:0xf bank_mask:0xf
	v_mov_b32_dpp v99, v93 row_shr:1 row_mask:0xf bank_mask:0xf
	v_mov_b32_dpp v115, v80 row_ror:15 row_mask:0xf bank_mask:0xf
	v_cndmask_b32_e32 v118, 0, v105, vcc
	v_cndmask_b32_e64 v105, 0, v111, s[4:5]
	v_mov_b32_dpp v115, v88 row_shl:1 row_mask:0xf bank_mask:0xf
	v_fma_f32 v115, v152, v115, v156
	v_fmac_f32_e32 v115, v140, v88
	v_fmac_f32_e32 v115, v136, v102
	v_cndmask_b32_e64 v111, 0, v114, s[4:5]
	v_mov_b32_dpp v102, v85 row_ror:15 row_mask:0xf bank_mask:0xf
	v_cndmask_b32_e32 v98, 0, v98, vcc
	v_mov_b32_dpp v114, v84 row_ror:15 row_mask:0xf bank_mask:0xf
	v_mov_b32_dpp v102, v93 row_shl:1 row_mask:0xf bank_mask:0xf
	v_fma_f32 v102, v149, v102, v129
	v_fmac_f32_e32 v102, v145, v93
	v_fmac_f32_e32 v102, v133, v99
	v_mul_f32_e32 v99, 0xbfb8aa3b, v102
	v_exp_f32_e32 v99, v99
	v_mov_b32_dpp v114, v92 row_shl:1 row_mask:0xf bank_mask:0xf
	v_fma_f32 v114, v148, v114, v128
	v_mov_b32_dpp v98, v92 row_shr:1 row_mask:0xf bank_mask:0xf
	v_fmac_f32_e32 v114, v144, v92
	v_fmac_f32_e32 v114, v132, v98
	v_add_f32_e32 v99, 1.0, v99
	v_mul_f32_e32 v98, 0xbfb8aa3b, v114
	v_rcp_f32_e32 v99, v99
	v_exp_f32_e32 v98, v98
	v_cndmask_b32_e32 v100, 0, v100, vcc
	v_cndmask_b32_e32 v103, 0, v103, vcc
	v_mul_f32_e32 v99, v102, v99
	v_add_f32_e32 v98, 1.0, v98
	v_rcp_f32_e32 v98, v98
	v_mov_b32_dpp v102, v86 row_ror:15 row_mask:0xf bank_mask:0xf
	v_mov_b32_dpp v100, v94 row_shr:1 row_mask:0xf bank_mask:0xf
	v_mov_b32_dpp v103, v89 row_shr:1 row_mask:0xf bank_mask:0xf
	v_mov_b32_dpp v102, v94 row_shl:1 row_mask:0xf bank_mask:0xf
	v_fma_f32 v102, v150, v102, v130
	v_fmac_f32_e32 v102, v146, v94
	v_fmac_f32_e32 v102, v134, v100
	v_mul_f32_e32 v98, v114, v98
	v_mul_f32_e32 v100, 0xbfb8aa3b, v102
	v_exp_f32_e32 v100, v100
	v_mov_b32_dpp v114, v81 row_ror:15 row_mask:0xf bank_mask:0xf
	v_cndmask_b32_e32 v119, 0, v104, vcc
	v_cndmask_b32_e32 v101, 0, v101, vcc
	v_mov_b32_dpp v114, v89 row_shl:1 row_mask:0xf bank_mask:0xf
	v_fma_f32 v114, v153, v114, v157
	v_fmac_f32_e32 v114, v141, v89
	v_fmac_f32_e32 v114, v137, v103
	v_add_f32_e32 v100, 1.0, v100
	v_rcp_f32_e32 v100, v100
	v_mov_b32_dpp v103, v82 row_ror:15 row_mask:0xf bank_mask:0xf
	v_mov_b32_dpp v119, v90 row_shr:1 row_mask:0xf bank_mask:0xf
	v_mov_b32_dpp v101, v95 row_shr:1 row_mask:0xf bank_mask:0xf
	v_mov_b32_dpp v103, v90 row_shl:1 row_mask:0xf bank_mask:0xf
	v_fma_f32 v103, v154, v103, v158
	v_fmac_f32_e32 v103, v142, v90
	v_fmac_f32_e32 v103, v138, v119
	v_mul_f32_e32 v100, v102, v100
	v_mul_f32_e32 v102, v103, v100
	v_mov_b32_dpp v118, v91 row_shr:1 row_mask:0xf bank_mask:0xf
	v_mov_b32_dpp v100, v87 row_ror:15 row_mask:0xf bank_mask:0xf
	v_mov_b32_dpp v103, v83 row_ror:15 row_mask:0xf bank_mask:0xf
	v_mul_f32_e32 v98, v115, v98
	v_mov_b32_dpp v100, v95 row_shl:1 row_mask:0xf bank_mask:0xf
	v_fma_f32 v100, v151, v100, v131
	v_fmac_f32_e32 v100, v147, v95
	v_fmac_f32_e32 v100, v135, v101
	v_mul_f32_e32 v101, 0xbfb8aa3b, v100
	v_exp_f32_e32 v101, v101
	v_mov_b32_dpp v103, v91 row_shl:1 row_mask:0xf bank_mask:0xf
	v_fma_f32 v103, v155, v103, v159
	v_fmac_f32_e32 v103, v143, v91
	v_add_f32_e32 v101, 1.0, v101
	v_rcp_f32_e32 v101, v101
	v_fmac_f32_e32 v103, v139, v118
	s_mov_b32 s3, 0xb0000
	v_mul_f32_e32 v99, v114, v99
	v_mul_f32_e32 v100, v100, v101
	v_mul_f32_e32 v101, v103, v100
	v_cvt_pk_bf16_f32 v100, v98, v99
	v_add_co_u32_e64 v98, s[8:9], s3, v172
	v_cvt_pk_bf16_f32 v101, v102, v101
	s_mov_b32 s3, 0xc6000
	s_nop 0
	v_addc_co_u32_e64 v99, s[8:9], 0, v173, s[8:9]
	flat_store_dwordx2 v[98:99], v[100:101]
	v_mov_b32_dpp v110, v72 row_shl:1 row_mask:0xf bank_mask:0xf
	v_mov_b32_dpp v100, v92 row_ror:1 row_mask:0xf bank_mask:0xf
	v_mov_b32_dpp v101, v68 row_ror:15 row_mask:0xf bank_mask:0xf
	s_nop 0
	v_mov_b32_dpp v100, v84 row_shr:1 row_mask:0xf bank_mask:0xf
	v_mov_b32_dpp v92, v88 row_ror:1 row_mask:0xf bank_mask:0xf
	v_mov_b32_dpp v101, v80 row_shl:1 row_mask:0xf bank_mask:0xf
	v_fma_f32 v101, v152, v101, v156
	v_mov_b32_dpp v88, v76 row_ror:15 row_mask:0xf bank_mask:0xf
	v_mov_b32_dpp v92, v80 row_shr:1 row_mask:0xf bank_mask:0xf
	v_fmac_f32_e32 v101, v140, v80
	v_mov_b32_dpp v88, v84 row_shl:1 row_mask:0xf bank_mask:0xf
	v_fma_f32 v88, v148, v88, v128
	v_fmac_f32_e32 v88, v144, v84
	v_fmac_f32_e32 v88, v132, v100
	v_mul_f32_e32 v100, 0xbfb8aa3b, v88
	v_fmac_f32_e32 v101, v136, v92
	v_exp_f32_e32 v100, v100
	v_mov_b32_dpp v111, v64 row_shl:1 row_mask:0xf bank_mask:0xf
	v_mov_b32_dpp v92, v93 row_ror:1 row_mask:0xf bank_mask:0xf
	v_add_f32_e32 v100, 1.0, v100
	v_rcp_f32_e32 v100, v100
	v_mov_b32_dpp v93, v89 row_ror:1 row_mask:0xf bank_mask:0xf
	v_mov_b32_dpp v92, v85 row_shr:1 row_mask:0xf bank_mask:0xf
	v_mul_f32_e32 v88, v88, v100
	v_mov_b32_dpp v89, v77 row_ror:15 row_mask:0xf bank_mask:0xf
	v_mov_b32_dpp v93, v81 row_shr:1 row_mask:0xf bank_mask:0xf
	s_nop 0
	v_mov_b32_dpp v89, v85 row_shl:1 row_mask:0xf bank_mask:0xf
	v_fma_f32 v89, v149, v89, v129
	v_fmac_f32_e32 v89, v145, v85
	v_fmac_f32_e32 v89, v133, v92
	v_mul_f32_e32 v92, 0xbfb8aa3b, v89
	v_exp_f32_e32 v92, v92
	v_mov_b32_dpp v100, v69 row_ror:15 row_mask:0xf bank_mask:0xf
	v_mul_f32_e32 v88, v101, v88
	v_cndmask_b32_e64 v109, 0, v109, s[4:5]
	v_mov_b32_dpp v100, v81 row_shl:1 row_mask:0xf bank_mask:0xf
	v_add_f32_e32 v92, 1.0, v92
	v_fma_f32 v100, v153, v100, v157
	v_rcp_f32_e32 v92, v92
	v_fmac_f32_e32 v100, v141, v81
	v_fmac_f32_e32 v100, v137, v93
	v_mul_f32_e32 v89, v89, v92
	v_mov_b32_dpp v93, v90 row_ror:1 row_mask:0xf bank_mask:0xf
	v_mov_b32_dpp v92, v94 row_ror:1 row_mask:0xf bank_mask:0xf
	v_mov_b32_dpp v90, v78 row_ror:15 row_mask:0xf bank_mask:0xf
	s_nop 0
	v_mov_b32_dpp v92, v86 row_shr:1 row_mask:0xf bank_mask:0xf
	v_mov_b32_dpp v94, v70 row_ror:15 row_mask:0xf bank_mask:0xf
	v_mov_b32_dpp v90, v86 row_shl:1 row_mask:0xf bank_mask:0xf
	v_fma_f32 v90, v150, v90, v130
	v_fmac_f32_e32 v90, v146, v86
	v_fmac_f32_e32 v90, v134, v92
	v_mul_f32_e32 v92, 0xbfb8aa3b, v90
	v_exp_f32_e32 v92, v92
	v_mov_b32_dpp v94, v82 row_shl:1 row_mask:0xf bank_mask:0xf
	v_fma_f32 v94, v154, v94, v158
	v_mov_b32_dpp v93, v82 row_shr:1 row_mask:0xf bank_mask:0xf
	v_add_f32_e32 v92, 1.0, v92
	v_rcp_f32_e32 v92, v92
	v_fmac_f32_e32 v94, v142, v82
	v_fmac_f32_e32 v94, v138, v93
	v_mul_f32_e32 v90, v90, v92
	v_mov_b32_dpp v93, v91 row_ror:1 row_mask:0xf bank_mask:0xf
	v_mov_b32_dpp v92, v95 row_ror:1 row_mask:0xf bank_mask:0xf
	v_mul_f32_e32 v90, v94, v90
	v_mov_b32_dpp v91, v79 row_ror:15 row_mask:0xf bank_mask:0xf
	v_mov_b32_dpp v92, v87 row_shr:1 row_mask:0xf bank_mask:0xf
	s_nop 0
	v_mov_b32_dpp v91, v87 row_shl:1 row_mask:0xf bank_mask:0xf
	v_fma_f32 v91, v151, v91, v131
	v_fmac_f32_e32 v91, v147, v87
	v_fmac_f32_e32 v91, v135, v92
	v_mul_f32_e32 v92, 0xbfb8aa3b, v91
	v_exp_f32_e32 v92, v92
	v_mov_b32_dpp v94, v71 row_ror:15 row_mask:0xf bank_mask:0xf
	v_mul_f32_e32 v89, v100, v89
	v_mov_b32_dpp v93, v83 row_shr:1 row_mask:0xf bank_mask:0xf
	v_add_f32_e32 v92, 1.0, v92
	v_rcp_f32_e32 v92, v92
	v_mov_b32_dpp v94, v83 row_shl:1 row_mask:0xf bank_mask:0xf
	v_fma_f32 v94, v155, v94, v159
	v_fmac_f32_e32 v94, v143, v83
	v_add_co_u32_e64 v100, s[8:9], s3, v172
	v_fmac_f32_e32 v94, v139, v93
	v_mul_f32_e32 v91, v91, v92
	v_cvt_pk_bf16_f32 v88, v88, v89
	v_addc_co_u32_e64 v101, s[8:9], 0, v173, s[8:9]
	v_mul_f32_e32 v91, v94, v91
	v_cvt_pk_bf16_f32 v89, v90, v91
	flat_store_dwordx2 v[100:101], v[88:89]
	s_mov_b32 s3, 0xdc000
	v_mov_b32_dpp v88, v84 row_ror:1 row_mask:0xf bank_mask:0xf
	v_mov_b32_dpp v89, v64 row_ror:15 row_mask:0xf bank_mask:0xf
	s_nop 0
	v_mov_b32_dpp v88, v76 row_shr:1 row_mask:0xf bank_mask:0xf
	v_mov_b32_dpp v84, v80 row_ror:1 row_mask:0xf bank_mask:0xf
	v_mov_b32_dpp v89, v68 row_shl:1 row_mask:0xf bank_mask:0xf
	v_fma_f32 v89, v152, v89, v156
	v_mov_b32_dpp v80, v72 row_ror:15 row_mask:0xf bank_mask:0xf
	v_mov_b32_dpp v84, v68 row_shr:1 row_mask:0xf bank_mask:0xf
	v_fmac_f32_e32 v89, v140, v68
	v_mov_b32_dpp v80, v76 row_shl:1 row_mask:0xf bank_mask:0xf
	v_fma_f32 v80, v148, v80, v128
	v_fmac_f32_e32 v80, v144, v76
	v_fmac_f32_e32 v80, v132, v88
	v_mul_f32_e32 v88, 0xbfb8aa3b, v80
	v_fmac_f32_e32 v89, v136, v84
	v_exp_f32_e32 v88, v88
	v_add_co_u32_e64 v102, s[8:9], s3, v172
	v_mov_b32_dpp v84, v85 row_ror:1 row_mask:0xf bank_mask:0xf
	v_add_f32_e32 v88, 1.0, v88
	v_rcp_f32_e32 v88, v88
	v_mov_b32_dpp v85, v81 row_ror:1 row_mask:0xf bank_mask:0xf
	v_mov_b32_dpp v84, v77 row_shr:1 row_mask:0xf bank_mask:0xf
	v_mul_f32_e32 v80, v80, v88
	v_mov_b32_dpp v81, v73 row_ror:15 row_mask:0xf bank_mask:0xf
	v_mov_b32_dpp v85, v69 row_shr:1 row_mask:0xf bank_mask:0xf
	s_nop 0
	v_mov_b32_dpp v81, v77 row_shl:1 row_mask:0xf bank_mask:0xf
	v_fma_f32 v81, v149, v81, v129
	v_fmac_f32_e32 v81, v145, v77
	v_fmac_f32_e32 v81, v133, v84
	v_mul_f32_e32 v84, 0xbfb8aa3b, v81
	v_exp_f32_e32 v84, v84
	v_mov_b32_dpp v88, v65 row_ror:15 row_mask:0xf bank_mask:0xf
	v_mul_f32_e32 v80, v89, v80
	v_addc_co_u32_e64 v103, s[8:9], 0, v173, s[8:9]
	v_mov_b32_dpp v88, v69 row_shl:1 row_mask:0xf bank_mask:0xf
	v_add_f32_e32 v84, 1.0, v84
	v_fma_f32 v88, v153, v88, v157
	v_rcp_f32_e32 v84, v84
	v_fmac_f32_e32 v88, v141, v69
	v_fmac_f32_e32 v88, v137, v85
	v_mul_f32_e32 v81, v81, v84
	v_mov_b32_dpp v85, v82 row_ror:1 row_mask:0xf bank_mask:0xf
	v_mov_b32_dpp v84, v86 row_ror:1 row_mask:0xf bank_mask:0xf
	v_mov_b32_dpp v82, v74 row_ror:15 row_mask:0xf bank_mask:0xf
	s_nop 0
	v_mov_b32_dpp v84, v78 row_shr:1 row_mask:0xf bank_mask:0xf
	v_mov_b32_dpp v86, v66 row_ror:15 row_mask:0xf bank_mask:0xf
	v_mov_b32_dpp v82, v78 row_shl:1 row_mask:0xf bank_mask:0xf
	v_fma_f32 v82, v150, v82, v130
	v_fmac_f32_e32 v82, v146, v78
	v_fmac_f32_e32 v82, v134, v84
	v_mul_f32_e32 v84, 0xbfb8aa3b, v82
	v_exp_f32_e32 v84, v84
	v_mov_b32_dpp v86, v70 row_shl:1 row_mask:0xf bank_mask:0xf
	v_fma_f32 v86, v154, v86, v158
	v_mov_b32_dpp v85, v70 row_shr:1 row_mask:0xf bank_mask:0xf
	v_add_f32_e32 v84, 1.0, v84
	v_rcp_f32_e32 v84, v84
	v_fmac_f32_e32 v86, v142, v70
	v_fmac_f32_e32 v86, v138, v85
	v_mul_f32_e32 v82, v82, v84
	v_mov_b32_dpp v85, v83 row_ror:1 row_mask:0xf bank_mask:0xf
	v_mov_b32_dpp v84, v87 row_ror:1 row_mask:0xf bank_mask:0xf
	v_mul_f32_e32 v82, v86, v82
	v_mov_b32_dpp v83, v75 row_ror:15 row_mask:0xf bank_mask:0xf
	v_mov_b32_dpp v84, v79 row_shr:1 row_mask:0xf bank_mask:0xf
	s_nop 0
	v_mov_b32_dpp v83, v79 row_shl:1 row_mask:0xf bank_mask:0xf
	v_fma_f32 v83, v151, v83, v131
	v_fmac_f32_e32 v83, v147, v79
	v_fmac_f32_e32 v83, v135, v84
	v_mul_f32_e32 v84, 0xbfb8aa3b, v83
	v_exp_f32_e32 v84, v84
	v_mov_b32_dpp v86, v67 row_ror:15 row_mask:0xf bank_mask:0xf
	v_mov_b32_dpp v85, v71 row_shr:1 row_mask:0xf bank_mask:0xf
	v_mul_f32_e32 v81, v88, v81
	v_add_f32_e32 v84, 1.0, v84
	v_rcp_f32_e32 v84, v84
	v_mov_b32_dpp v86, v71 row_shl:1 row_mask:0xf bank_mask:0xf
	v_fma_f32 v86, v155, v86, v159
	v_fmac_f32_e32 v86, v143, v71
	v_fmac_f32_e32 v86, v139, v85
	v_mul_f32_e32 v83, v83, v84
	v_cvt_pk_bf16_f32 v80, v80, v81
	v_mul_f32_e32 v83, v86, v83
	v_cvt_pk_bf16_f32 v81, v82, v83
	flat_store_dwordx2 v[102:103], v[80:81]
	v_fma_f32 v81, v148, v110, v128
	v_fmac_f32_e32 v81, v144, v72
	v_mov_b32_dpp v80, v76 row_ror:1 row_mask:0xf bank_mask:0xf
	v_mov_b32_dpp v109, v73 row_shl:1 row_mask:0xf bank_mask:0xf
	s_nop 0
	v_mov_b32_dpp v80, v72 row_shr:1 row_mask:0xf bank_mask:0xf
	v_fmac_f32_e32 v81, v132, v80
	v_mul_f32_e32 v72, 0xbfb8aa3b, v81
	v_exp_f32_e32 v72, v72
	v_mov_b32_dpp v76, v68 row_ror:1 row_mask:0xf bank_mask:0xf
	v_mov_b32_dpp v108, v65 row_shl:1 row_mask:0xf bank_mask:0xf
	v_mov_b32_dpp v107, v74 row_shl:1 row_mask:0xf bank_mask:0xf
	v_add_f32_e32 v68, 1.0, v72
	v_rcp_f32_e32 v68, v68
	v_fma_f32 v72, v152, v111, v156
	v_mov_b32_dpp v76, v64 row_shr:1 row_mask:0xf bank_mask:0xf
	v_fmac_f32_e32 v72, v140, v64
	v_mul_f32_e32 v64, v81, v68
	v_fmac_f32_e32 v72, v136, v76
	v_fma_f32 v76, v149, v109, v129
	v_mov_b32_dpp v68, v77 row_ror:1 row_mask:0xf bank_mask:0xf
	v_fmac_f32_e32 v76, v145, v73
	v_mul_f32_e32 v64, v72, v64
	v_mov_b32_dpp v68, v73 row_shr:1 row_mask:0xf bank_mask:0xf
	v_fmac_f32_e32 v76, v133, v68
	v_mul_f32_e32 v68, 0xbfb8aa3b, v76
	v_exp_f32_e32 v68, v68
	v_cndmask_b32_e64 v106, 0, v116, s[4:5]
	v_mov_b32_dpp v105, v75 row_shl:1 row_mask:0xf bank_mask:0xf
	v_add_f32_e32 v68, 1.0, v68
	v_rcp_f32_e32 v68, v68
	v_mov_b32_dpp v72, v69 row_ror:1 row_mask:0xf bank_mask:0xf
	v_fma_f32 v69, v153, v108, v157
	v_fmac_f32_e32 v69, v141, v65
	v_mov_b32_dpp v72, v65 row_shr:1 row_mask:0xf bank_mask:0xf
	v_mul_f32_e32 v65, v76, v68
	v_fmac_f32_e32 v69, v137, v72
	v_fma_f32 v72, v150, v107, v130
	v_mov_b32_dpp v68, v78 row_ror:1 row_mask:0xf bank_mask:0xf
	v_fmac_f32_e32 v72, v146, v74
	v_mul_f32_e32 v65, v69, v65
	v_mov_b32_dpp v68, v74 row_shr:1 row_mask:0xf bank_mask:0xf
	v_fmac_f32_e32 v72, v134, v68
	v_mul_f32_e32 v68, 0xbfb8aa3b, v72
	v_exp_f32_e32 v68, v68
	v_mov_b32_dpp v106, v66 row_shl:1 row_mask:0xf bank_mask:0xf
	v_fmac_f32_e32 v131, v151, v105
	v_add_f32_e32 v68, 1.0, v68
	v_rcp_f32_e32 v68, v68
	v_mov_b32_dpp v69, v70 row_ror:1 row_mask:0xf bank_mask:0xf
	v_fma_f32 v70, v154, v106, v158
	v_fmac_f32_e32 v70, v142, v66
	v_mov_b32_dpp v69, v66 row_shr:1 row_mask:0xf bank_mask:0xf
	v_mul_f32_e32 v66, v72, v68
	v_fmac_f32_e32 v131, v147, v75
	v_cndmask_b32_e64 v104, 0, v117, s[4:5]
	v_mov_b32_dpp v68, v79 row_ror:1 row_mask:0xf bank_mask:0xf
	v_fmac_f32_e32 v70, v138, v69
	s_nop 0
	v_mov_b32_dpp v68, v75 row_shr:1 row_mask:0xf bank_mask:0xf
	v_fmac_f32_e32 v131, v135, v68
	v_mul_f32_e32 v68, 0xbfb8aa3b, v131
	v_exp_f32_e32 v68, v68
	v_mov_b32_dpp v104, v67 row_shl:1 row_mask:0xf bank_mask:0xf
	v_mov_b32_dpp v69, v71 row_ror:1 row_mask:0xf bank_mask:0xf
	v_fmac_f32_e32 v159, v155, v104
	v_add_f32_e32 v68, 1.0, v68
	v_rcp_f32_e32 v68, v68
	s_mov_b32 s3, 0xf2000
	v_mov_b32_dpp v69, v67 row_shr:1 row_mask:0xf bank_mask:0xf
	v_fmac_f32_e32 v159, v143, v67
	v_add_co_u32_e64 v104, s[8:9], s3, v172
	v_fmac_f32_e32 v159, v139, v69
	v_mul_f32_e32 v67, v131, v68
	v_addc_co_u32_e64 v105, s[8:9], 0, v173, s[8:9]
	v_mul_f32_e32 v66, v70, v66
	v_mul_f32_e32 v67, v159, v67
	v_cvt_pk_bf16_f32 v64, v64, v65
	v_cvt_pk_bf16_f32 v65, v66, v67
	flat_store_dwordx2 v[104:105], v[64:65]
	v_or_b32_e32 v64, 4, v174
	v_ashrrev_i32_e32 v65, 31, v64
	v_lshlrev_b64 v[64:65], 2, v[64:65]
	v_lshl_add_u64 v[66:67], s[52:53], 0, v[64:65]
	global_load_dwordx4 v[76:79], v[178:179], off offset:16
	global_load_dwordx4 v[80:83], v[66:67], off
	v_lshl_add_u64 v[64:65], s[68:69], 0, v[64:65]
	global_load_dwordx4 v[84:87], v[64:65], off
	s_nop 0
	global_load_dwordx4 v[64:67], v[182:183], off offset:16
	global_load_dwordx4 v[68:71], v[184:185], off offset:3088
	global_load_dwordx4 v[72:75], v[186:187], off offset:3088
	global_load_dwordx4 v[92:95], v[176:177], off offset:3088
	global_load_dwordx4 v[88:91], v[180:181], off offset:3088
	v_add_u32_e32 v106, 0xffffff40, v212
	v_subrev_u32_e32 v110, 64, v212
	ds_read_b128 v[106:109], v106
	ds_read_b128 v[122:125], v110
	ds_read_b128 v[126:129], v212 offset:64
	ds_read_b128 v[130:133], v212 offset:192
	s_waitcnt lgkmcnt(0)
	v_cndmask_b32_e64 v117, 0, v125, s[6:7]
	v_cndmask_b32_e32 v115, 0, v126, vcc
	v_mov_b32_dpp v125, v52 row_ror:15 row_mask:0xf bank_mask:0xf
	v_cndmask_b32_e64 v118, 0, v106, s[6:7]
	v_mov_b32_dpp v126, v48 row_ror:15 row_mask:0xf bank_mask:0xf
	v_mov_b32_dpp v125, v60 row_shl:1 row_mask:0xf bank_mask:0xf
	v_mov_b32_dpp v118, v60 row_shr:1 row_mask:0xf bank_mask:0xf
	v_mov_b32_dpp v126, v56 row_shl:1 row_mask:0xf bank_mask:0xf
	v_cndmask_b32_e64 v122, 0, v122, s[6:7]
	v_cndmask_b32_e64 v119, 0, v107, s[6:7]
	v_cndmask_b32_e64 v123, 0, v123, s[6:7]
	v_mov_b32_dpp v122, v56 row_shr:1 row_mask:0xf bank_mask:0xf
	v_mov_b32_dpp v119, v61 row_shr:1 row_mask:0xf bank_mask:0xf
	v_mov_b32_dpp v123, v57 row_shr:1 row_mask:0xf bank_mask:0xf
	v_cndmask_b32_e64 v134, 0, v108, s[6:7]
	v_cndmask_b32_e64 v124, 0, v124, s[6:7]
	v_cndmask_b32_e64 v116, 0, v109, s[6:7]
	v_mov_b32_dpp v134, v62 row_shr:1 row_mask:0xf bank_mask:0xf
	v_mov_b32_dpp v124, v58 row_shr:1 row_mask:0xf bank_mask:0xf
	v_mov_b32_dpp v116, v63 row_shr:1 row_mask:0xf bank_mask:0xf
	v_mov_b32_dpp v117, v59 row_shr:1 row_mask:0xf bank_mask:0xf
	v_mov_b32_dpp v115, v36 row_shl:1 row_mask:0xf bank_mask:0xf
	v_cndmask_b32_e32 v114, 0, v130, vcc
	v_cndmask_b32_e32 v111, 0, v127, vcc
	v_cndmask_b32_e32 v110, 0, v131, vcc
	v_mov_b32_dpp v114, v32 row_shl:1 row_mask:0xf bank_mask:0xf
	v_mov_b32_dpp v111, v37 row_shl:1 row_mask:0xf bank_mask:0xf
	v_mov_b32_dpp v110, v33 row_shl:1 row_mask:0xf bank_mask:0xf
	v_cndmask_b32_e32 v109, 0, v128, vcc
	v_cndmask_b32_e32 v108, 0, v132, vcc
	v_cndmask_b32_e32 v107, 0, v129, vcc
	v_mov_b32_dpp v109, v38 row_shl:1 row_mask:0xf bank_mask:0xf
	v_mov_b32_dpp v108, v34 row_shl:1 row_mask:0xf bank_mask:0xf
	v_mov_b32_dpp v107, v39 row_shl:1 row_mask:0xf bank_mask:0xf
	v_cndmask_b32_e32 v106, 0, v133, vcc
	s_waitcnt vmcnt(0)
	v_fma_f32 v125, v84, v125, v64
	v_mov_b32_dpp v106, v35 row_shl:1 row_mask:0xf bank_mask:0xf
	v_fmac_f32_e32 v125, v80, v60
	v_fmac_f32_e32 v125, v76, v118
	v_fma_f32 v118, v92, v126, v88
	v_fmac_f32_e32 v118, v72, v56
	v_fmac_f32_e32 v118, v68, v122
	v_mul_f32_e32 v122, 0xbfb8aa3b, v125
	v_exp_f32_e32 v122, v122
	s_nop 0
	v_add_f32_e32 v122, 1.0, v122
	v_rcp_f32_e32 v122, v122
	s_nop 0
	v_mul_f32_e32 v122, v125, v122
	v_mul_f32_e32 v118, v118, v122
	s_nop 0
	v_mov_b32_dpp v122, v53 row_ror:15 row_mask:0xf bank_mask:0xf
	v_mov_b32_dpp v125, v49 row_ror:15 row_mask:0xf bank_mask:0xf
	s_nop 0
	v_mov_b32_dpp v122, v61 row_shl:1 row_mask:0xf bank_mask:0xf
	v_fma_f32 v122, v85, v122, v65
	v_mov_b32_dpp v125, v57 row_shl:1 row_mask:0xf bank_mask:0xf
	v_fmac_f32_e32 v122, v81, v61
	v_fmac_f32_e32 v122, v77, v119
	v_fma_f32 v119, v93, v125, v89
	v_fmac_f32_e32 v119, v73, v57
	v_fmac_f32_e32 v119, v69, v123
	v_mul_f32_e32 v123, 0xbfb8aa3b, v122
	v_exp_f32_e32 v123, v123
	s_nop 0
	v_add_f32_e32 v123, 1.0, v123
	v_rcp_f32_e32 v123, v123
	s_nop 0
	v_mul_f32_e32 v122, v122, v123
	v_mul_f32_e32 v119, v119, v122
	s_nop 0
	v_mov_b32_dpp v122, v54 row_ror:15 row_mask:0xf bank_mask:0xf
	v_mov_b32_dpp v123, v50 row_ror:15 row_mask:0xf bank_mask:0xf
	s_nop 0
	v_mov_b32_dpp v122, v62 row_shl:1 row_mask:0xf bank_mask:0xf
	v_mov_b32_dpp v123, v58 row_shl:1 row_mask:0xf bank_mask:0xf
	v_fma_f32 v122, v86, v122, v66
	v_fmac_f32_e32 v122, v82, v62
	v_fma_f32 v123, v94, v123, v90
	v_fmac_f32_e32 v122, v78, v134
	v_fmac_f32_e32 v123, v74, v58
	v_fmac_f32_e32 v123, v70, v124
	v_mul_f32_e32 v124, 0xbfb8aa3b, v122
	v_exp_f32_e32 v124, v124
	s_nop 0
	v_add_f32_e32 v124, 1.0, v124
	v_rcp_f32_e32 v124, v124
	s_nop 0
	v_mul_f32_e32 v122, v122, v124
	v_mul_f32_e32 v122, v123, v122
	s_nop 0
	v_mov_b32_dpp v123, v55 row_ror:15 row_mask:0xf bank_mask:0xf
	v_mov_b32_dpp v124, v51 row_ror:15 row_mask:0xf bank_mask:0xf
	s_nop 0
	v_mov_b32_dpp v123, v63 row_shl:1 row_mask:0xf bank_mask:0xf
	v_fma_f32 v123, v87, v123, v67
	v_mov_b32_dpp v124, v59 row_shl:1 row_mask:0xf bank_mask:0xf
	v_fmac_f32_e32 v123, v83, v63
	v_fmac_f32_e32 v123, v79, v116
	v_fma_f32 v116, v95, v124, v91
	v_fmac_f32_e32 v116, v75, v59
	v_fmac_f32_e32 v116, v71, v117
	v_mul_f32_e32 v117, 0xbfb8aa3b, v123
	v_exp_f32_e32 v117, v117
	s_nop 0
	v_add_f32_e32 v117, 1.0, v117
	v_rcp_f32_e32 v117, v117
	s_nop 0
	v_mul_f32_e32 v117, v123, v117
	v_mul_f32_e32 v117, v116, v117
	v_cvt_pk_bf16_f32 v116, v118, v119
	v_cvt_pk_bf16_f32 v117, v122, v117
	flat_store_dwordx2 v[172:173], v[116:117] offset:8
	s_nop 0
	v_mov_b32_dpp v116, v60 row_ror:1 row_mask:0xf bank_mask:0xf
	v_mov_b32_dpp v117, v40 row_ror:15 row_mask:0xf bank_mask:0xf
	s_nop 0
	v_mov_b32_dpp v116, v52 row_shr:1 row_mask:0xf bank_mask:0xf
	v_mov_b32_dpp v60, v56 row_ror:1 row_mask:0xf bank_mask:0xf
	v_mov_b32_dpp v117, v48 row_shl:1 row_mask:0xf bank_mask:0xf
	s_nop 0
	v_mov_b32_dpp v60, v48 row_shr:1 row_mask:0xf bank_mask:0xf
	v_mov_b32_dpp v56, v44 row_ror:15 row_mask:0xf bank_mask:0xf
	s_nop 1
	v_mov_b32_dpp v56, v52 row_shl:1 row_mask:0xf bank_mask:0xf
	v_fma_f32 v56, v84, v56, v64
	v_fmac_f32_e32 v56, v80, v52
	v_fmac_f32_e32 v56, v76, v116
	v_fma_f32 v116, v92, v117, v88
	v_fmac_f32_e32 v116, v72, v48
	v_fmac_f32_e32 v116, v68, v60
	v_mul_f32_e32 v60, 0xbfb8aa3b, v56
	v_exp_f32_e32 v60, v60
	s_nop 0
	v_add_f32_e32 v60, 1.0, v60
	v_rcp_f32_e32 v60, v60
	s_nop 0
	v_mul_f32_e32 v56, v56, v60
	v_mul_f32_e32 v56, v116, v56
	v_mov_b32_dpp v60, v61 row_ror:1 row_mask:0xf bank_mask:0xf
	v_mov_b32_dpp v116, v41 row_ror:15 row_mask:0xf bank_mask:0xf
	s_nop 0
	v_mov_b32_dpp v60, v53 row_shr:1 row_mask:0xf bank_mask:0xf
	v_mov_b32_dpp v61, v57 row_ror:1 row_mask:0xf bank_mask:0xf
	v_mov_b32_dpp v116, v49 row_shl:1 row_mask:0xf bank_mask:0xf
	s_nop 0
	v_mov_b32_dpp v61, v49 row_shr:1 row_mask:0xf bank_mask:0xf
	v_mov_b32_dpp v57, v45 row_ror:15 row_mask:0xf bank_mask:0xf
	s_nop 1
	v_mov_b32_dpp v57, v53 row_shl:1 row_mask:0xf bank_mask:0xf
	v_fma_f32 v57, v85, v57, v65
	v_fmac_f32_e32 v57, v81, v53
	v_fmac_f32_e32 v57, v77, v60
	v_fma_f32 v60, v93, v116, v89
	v_fmac_f32_e32 v60, v73, v49
	v_fmac_f32_e32 v60, v69, v61
	v_mul_f32_e32 v61, 0xbfb8aa3b, v57
	v_exp_f32_e32 v61, v61
	s_nop 0
	v_add_f32_e32 v61, 1.0, v61
	v_rcp_f32_e32 v61, v61
	s_nop 0
	v_mul_f32_e32 v57, v57, v61
	v_mul_f32_e32 v57, v60, v57
	v_mov_b32_dpp v61, v58 row_ror:1 row_mask:0xf bank_mask:0xf
	v_mov_b32_dpp v60, v62 row_ror:1 row_mask:0xf bank_mask:0xf
	v_mov_b32_dpp v58, v46 row_ror:15 row_mask:0xf bank_mask:0xf
	s_nop 0
	v_mov_b32_dpp v60, v54 row_shr:1 row_mask:0xf bank_mask:0xf
	v_mov_b32_dpp v62, v42 row_ror:15 row_mask:0xf bank_mask:0xf
	v_mov_b32_dpp v58, v54 row_shl:1 row_mask:0xf bank_mask:0xf
	v_fma_f32 v58, v86, v58, v66
	v_mov_b32_dpp v62, v50 row_shl:1 row_mask:0xf bank_mask:0xf
	v_fmac_f32_e32 v58, v82, v54
	v_fmac_f32_e32 v58, v78, v60
	v_fma_f32 v60, v94, v62, v90
	v_mov_b32_dpp v61, v50 row_shr:1 row_mask:0xf bank_mask:0xf
	v_fmac_f32_e32 v60, v74, v50
	v_fmac_f32_e32 v60, v70, v61
	v_mul_f32_e32 v61, 0xbfb8aa3b, v58
	v_exp_f32_e32 v61, v61
	v_cvt_pk_bf16_f32 v56, v56, v57
	v_add_f32_e32 v61, 1.0, v61
	v_rcp_f32_e32 v61, v61
	v_mov_b32_dpp v62, v43 row_ror:15 row_mask:0xf bank_mask:0xf
	v_mul_f32_e32 v58, v58, v61
	v_mul_f32_e32 v58, v60, v58
	v_mov_b32_dpp v61, v59 row_ror:1 row_mask:0xf bank_mask:0xf
	v_mov_b32_dpp v60, v63 row_ror:1 row_mask:0xf bank_mask:0xf
	v_mov_b32_dpp v62, v51 row_shl:1 row_mask:0xf bank_mask:0xf
	v_mov_b32_dpp v59, v47 row_ror:15 row_mask:0xf bank_mask:0xf
	v_mov_b32_dpp v60, v55 row_shr:1 row_mask:0xf bank_mask:0xf
	v_mov_b32_dpp v61, v51 row_shr:1 row_mask:0xf bank_mask:0xf
	v_mov_b32_dpp v59, v55 row_shl:1 row_mask:0xf bank_mask:0xf
	v_fma_f32 v59, v87, v59, v67
	v_fmac_f32_e32 v59, v83, v55
	v_fmac_f32_e32 v59, v79, v60
	v_fma_f32 v60, v95, v62, v91
	v_fmac_f32_e32 v60, v75, v51
	v_fmac_f32_e32 v60, v71, v61
	v_mul_f32_e32 v61, 0xbfb8aa3b, v59
	v_exp_f32_e32 v61, v61
	s_nop 0
	v_add_f32_e32 v61, 1.0, v61
	v_rcp_f32_e32 v61, v61
	s_nop 0
	v_mul_f32_e32 v59, v59, v61
	v_mul_f32_e32 v59, v60, v59
	v_cvt_pk_bf16_f32 v57, v58, v59
	flat_store_dwordx2 v[120:121], v[56:57] offset:8
	s_nop 0
	v_mov_b32_dpp v56, v52 row_ror:1 row_mask:0xf bank_mask:0xf
	v_mov_b32_dpp v57, v32 row_ror:15 row_mask:0xf bank_mask:0xf
	s_nop 0
	v_mov_b32_dpp v56, v44 row_shr:1 row_mask:0xf bank_mask:0xf
	v_mov_b32_dpp v52, v48 row_ror:1 row_mask:0xf bank_mask:0xf
	v_mov_b32_dpp v57, v40 row_shl:1 row_mask:0xf bank_mask:0xf
	s_nop 0
	v_mov_b32_dpp v52, v40 row_shr:1 row_mask:0xf bank_mask:0xf
	v_mov_b32_dpp v48, v36 row_ror:15 row_mask:0xf bank_mask:0xf
	s_nop 1
	v_mov_b32_dpp v48, v44 row_shl:1 row_mask:0xf bank_mask:0xf
	v_fma_f32 v48, v84, v48, v64
	v_fmac_f32_e32 v48, v80, v44
	v_fmac_f32_e32 v48, v76, v56
	v_fma_f32 v56, v92, v57, v88
	v_fmac_f32_e32 v56, v72, v40
	v_fmac_f32_e32 v56, v68, v52
	v_mul_f32_e32 v52, 0xbfb8aa3b, v48
	v_exp_f32_e32 v52, v52
	s_nop 0
	v_add_f32_e32 v52, 1.0, v52
	v_rcp_f32_e32 v52, v52
	s_nop 0
	v_mul_f32_e32 v48, v48, v52
	v_mul_f32_e32 v48, v56, v48
	v_mov_b32_dpp v52, v53 row_ror:1 row_mask:0xf bank_mask:0xf
	v_mov_b32_dpp v56, v33 row_ror:15 row_mask:0xf bank_mask:0xf
	s_nop 0
	v_mov_b32_dpp v52, v45 row_shr:1 row_mask:0xf bank_mask:0xf
	v_mov_b32_dpp v53, v49 row_ror:1 row_mask:0xf bank_mask:0xf
	v_mov_b32_dpp v56, v41 row_shl:1 row_mask:0xf bank_mask:0xf
	s_nop 0
	v_mov_b32_dpp v53, v41 row_shr:1 row_mask:0xf bank_mask:0xf
	v_mov_b32_dpp v49, v37 row_ror:15 row_mask:0xf bank_mask:0xf
	s_nop 1
	v_mov_b32_dpp v49, v45 row_shl:1 row_mask:0xf bank_mask:0xf
	v_fma_f32 v49, v85, v49, v65
	v_fmac_f32_e32 v49, v81, v45
	v_fmac_f32_e32 v49, v77, v52
	v_fma_f32 v52, v93, v56, v89
	v_fmac_f32_e32 v52, v73, v41
	v_fmac_f32_e32 v52, v69, v53
	v_mul_f32_e32 v53, 0xbfb8aa3b, v49
	v_exp_f32_e32 v53, v53
	s_nop 0
	v_add_f32_e32 v53, 1.0, v53
	v_rcp_f32_e32 v53, v53
	s_nop 0
	v_mul_f32_e32 v49, v49, v53
	v_mul_f32_e32 v49, v52, v49
	v_mov_b32_dpp v53, v50 row_ror:1 row_mask:0xf bank_mask:0xf
	v_mov_b32_dpp v52, v54 row_ror:1 row_mask:0xf bank_mask:0xf
	v_mov_b32_dpp v50, v38 row_ror:15 row_mask:0xf bank_mask:0xf
	s_nop 0
	v_mov_b32_dpp v52, v46 row_shr:1 row_mask:0xf bank_mask:0xf
	v_mov_b32_dpp v54, v34 row_ror:15 row_mask:0xf bank_mask:0xf
	v_mov_b32_dpp v50, v46 row_shl:1 row_mask:0xf bank_mask:0xf
	v_fma_f32 v50, v86, v50, v66
	v_mov_b32_dpp v54, v42 row_shl:1 row_mask:0xf bank_mask:0xf
	v_fmac_f32_e32 v50, v82, v46
	v_fmac_f32_e32 v50, v78, v52
	v_fma_f32 v52, v94, v54, v90
	v_mov_b32_dpp v53, v42 row_shr:1 row_mask:0xf bank_mask:0xf
	v_fmac_f32_e32 v52, v74, v42
	v_fmac_f32_e32 v52, v70, v53
	v_mul_f32_e32 v53, 0xbfb8aa3b, v50
	v_exp_f32_e32 v53, v53
	v_cvt_pk_bf16_f32 v48, v48, v49
	v_add_f32_e32 v53, 1.0, v53
	v_rcp_f32_e32 v53, v53
	v_mov_b32_dpp v54, v35 row_ror:15 row_mask:0xf bank_mask:0xf
	v_mul_f32_e32 v50, v50, v53
	v_mul_f32_e32 v50, v52, v50
	v_mov_b32_dpp v53, v51 row_ror:1 row_mask:0xf bank_mask:0xf
	v_mov_b32_dpp v52, v55 row_ror:1 row_mask:0xf bank_mask:0xf
	v_mov_b32_dpp v54, v43 row_shl:1 row_mask:0xf bank_mask:0xf
	v_mov_b32_dpp v51, v39 row_ror:15 row_mask:0xf bank_mask:0xf
	v_mov_b32_dpp v52, v47 row_shr:1 row_mask:0xf bank_mask:0xf
	v_mov_b32_dpp v53, v43 row_shr:1 row_mask:0xf bank_mask:0xf
	v_mov_b32_dpp v51, v47 row_shl:1 row_mask:0xf bank_mask:0xf
	v_fma_f32 v51, v87, v51, v67
	v_fmac_f32_e32 v51, v83, v47
	v_fmac_f32_e32 v51, v79, v52
	v_fma_f32 v52, v95, v54, v91
	v_fmac_f32_e32 v52, v75, v43
	v_fmac_f32_e32 v52, v71, v53
	v_mul_f32_e32 v53, 0xbfb8aa3b, v51
	v_exp_f32_e32 v53, v53
	s_nop 0
	v_add_f32_e32 v53, 1.0, v53
	v_rcp_f32_e32 v53, v53
	s_nop 0
	v_mul_f32_e32 v51, v51, v53
	v_mul_f32_e32 v51, v52, v51
	v_cvt_pk_bf16_f32 v49, v50, v51
	flat_store_dwordx2 v[112:113], v[48:49] offset:8
	s_nop 1
	v_mov_b32_dpp v48, v44 row_ror:1 row_mask:0xf bank_mask:0xf
	s_nop 0
	s_nop 0
	v_mov_b32_dpp v48, v36 row_shr:1 row_mask:0xf bank_mask:0xf
	v_mov_b32_dpp v44, v40 row_ror:1 row_mask:0xf bank_mask:0xf
	v_fma_f32 v40, v84, v115, v64
	v_fmac_f32_e32 v40, v80, v36
	v_fmac_f32_e32 v40, v76, v48
	v_fma_f32 v36, v92, v114, v88
	v_mov_b32_dpp v44, v32 row_shr:1 row_mask:0xf bank_mask:0xf
	v_fmac_f32_e32 v36, v72, v32
	v_mul_f32_e32 v32, 0xbfb8aa3b, v40
	v_exp_f32_e32 v32, v32
	v_fmac_f32_e32 v36, v68, v44
	v_add_f32_e32 v32, 1.0, v32
	v_rcp_f32_e32 v32, v32
	s_nop 0
	v_mul_f32_e32 v32, v40, v32
	v_mul_f32_e32 v32, v36, v32
	s_nop 0
	v_mov_b32_dpp v36, v45 row_ror:1 row_mask:0xf bank_mask:0xf
	v_mov_b32_dpp v40, v41 row_ror:1 row_mask:0xf bank_mask:0xf
	v_fma_f32 v41, v85, v111, v65
	v_mov_b32_dpp v36, v37 row_shr:1 row_mask:0xf bank_mask:0xf
	v_fmac_f32_e32 v41, v81, v37
	v_fmac_f32_e32 v41, v77, v36
	v_fma_f32 v36, v93, v110, v89
	v_mov_b32_dpp v40, v33 row_shr:1 row_mask:0xf bank_mask:0xf
	v_fmac_f32_e32 v36, v73, v33
	v_mul_f32_e32 v33, 0xbfb8aa3b, v41
	v_exp_f32_e32 v33, v33
	v_fmac_f32_e32 v36, v69, v40
	v_fma_f32 v40, v86, v109, v66
	v_add_f32_e32 v33, 1.0, v33
	v_rcp_f32_e32 v33, v33
	v_fmac_f32_e32 v40, v82, v38
	v_mov_b32_dpp v37, v42 row_ror:1 row_mask:0xf bank_mask:0xf
	v_mul_f32_e32 v33, v41, v33
	v_mul_f32_e32 v33, v36, v33
	v_mov_b32_dpp v37, v34 row_shr:1 row_mask:0xf bank_mask:0xf
	v_cvt_pk_bf16_f32 v32, v32, v33
	s_nop 0
	v_mov_b32_dpp v36, v46 row_ror:1 row_mask:0xf bank_mask:0xf
	s_nop 1
	v_mov_b32_dpp v36, v38 row_shr:1 row_mask:0xf bank_mask:0xf
	v_fmac_f32_e32 v40, v78, v36
	v_fma_f32 v36, v94, v108, v90
	v_fmac_f32_e32 v36, v74, v34
	v_mul_f32_e32 v34, 0xbfb8aa3b, v40
	v_exp_f32_e32 v34, v34
	v_fmac_f32_e32 v36, v70, v37
	v_fma_f32 v38, v87, v107, v67
	v_add_f32_e32 v34, 1.0, v34
	v_rcp_f32_e32 v34, v34
	v_fmac_f32_e32 v38, v83, v39
	v_mov_b32_dpp v37, v43 row_ror:1 row_mask:0xf bank_mask:0xf
	v_mul_f32_e32 v34, v40, v34
	v_mul_f32_e32 v34, v36, v34
	v_mov_b32_dpp v37, v35 row_shr:1 row_mask:0xf bank_mask:0xf
	s_nop 0
	v_mov_b32_dpp v36, v47 row_ror:1 row_mask:0xf bank_mask:0xf
	s_nop 1
	v_mov_b32_dpp v36, v39 row_shr:1 row_mask:0xf bank_mask:0xf
	v_fmac_f32_e32 v38, v79, v36
	v_fma_f32 v36, v95, v106, v91
	v_fmac_f32_e32 v36, v75, v35
	v_mul_f32_e32 v35, 0xbfb8aa3b, v38
	v_exp_f32_e32 v35, v35
	v_fmac_f32_e32 v36, v71, v37
	v_add_f32_e32 v35, 1.0, v35
	v_rcp_f32_e32 v35, v35
	s_nop 0
	v_mul_f32_e32 v35, v38, v35
	v_mul_f32_e32 v35, v36, v35
	v_cvt_pk_bf16_f32 v33, v34, v35
	flat_store_dwordx2 v[96:97], v[32:33] offset:8
	ds_read_b128 v[32:35], v212 offset:320
	ds_read_b128 v[36:39], v212 offset:448
	ds_read_b128 v[40:43], v212 offset:576
	ds_read_b128 v[44:47], v212 offset:704
	s_waitcnt lgkmcnt(0)
	v_cndmask_b32_e32 v48, 0, v35, vcc
	v_cndmask_b32_e32 v51, 0, v32, vcc
	v_cndmask_b32_e64 v35, 0, v40, s[4:5]
	s_nop 0
	v_mov_b32_dpp v51, v28 row_shr:1 row_mask:0xf bank_mask:0xf
	v_cndmask_b32_e32 v52, 0, v39, vcc
	v_mov_b32_dpp v40, v20 row_ror:15 row_mask:0xf bank_mask:0xf
	v_cndmask_b32_e64 v39, 0, v42, s[4:5]
	v_cndmask_b32_e32 v54, 0, v37, vcc
	v_mov_b32_dpp v40, v28 row_shl:1 row_mask:0xf bank_mask:0xf
	v_fma_f32 v40, v84, v40, v64
	v_fmac_f32_e32 v40, v80, v28
	v_fmac_f32_e32 v40, v76, v51
	v_mul_f32_e32 v42, 0xbfb8aa3b, v40
	v_exp_f32_e32 v42, v42
	v_cndmask_b32_e64 v37, 0, v41, s[4:5]
	v_cndmask_b32_e32 v55, 0, v36, vcc
	v_add_f32_e32 v42, 1.0, v42
	v_mov_b32_dpp v41, v16 row_ror:15 row_mask:0xf bank_mask:0xf
	v_rcp_f32_e32 v42, v42
	v_mov_b32_dpp v55, v24 row_shr:1 row_mask:0xf bank_mask:0xf
	v_mov_b32_dpp v41, v24 row_shl:1 row_mask:0xf bank_mask:0xf
	v_fma_f32 v41, v92, v41, v88
	v_fmac_f32_e32 v41, v72, v24
	v_fmac_f32_e32 v41, v68, v55
	v_mul_f32_e32 v40, v40, v42
	v_mul_f32_e32 v40, v41, v40
	v_cndmask_b32_e32 v50, 0, v33, vcc
	v_cndmask_b32_e64 v33, 0, v43, s[4:5]
	v_mov_b32_dpp v41, v21 row_ror:15 row_mask:0xf bank_mask:0xf
	v_mov_b32_dpp v50, v29 row_shr:1 row_mask:0xf bank_mask:0xf
	s_nop 0
	v_mov_b32_dpp v41, v29 row_shl:1 row_mask:0xf bank_mask:0xf
	v_fma_f32 v41, v85, v41, v65
	v_fmac_f32_e32 v41, v81, v29
	v_fmac_f32_e32 v41, v77, v50
	v_mul_f32_e32 v43, 0xbfb8aa3b, v41
	v_exp_f32_e32 v43, v43
	v_mov_b32_dpp v42, v17 row_ror:15 row_mask:0xf bank_mask:0xf
	v_mov_b32_dpp v54, v25 row_shr:1 row_mask:0xf bank_mask:0xf
	v_cndmask_b32_e32 v49, 0, v34, vcc
	v_add_f32_e32 v43, 1.0, v43
	v_rcp_f32_e32 v43, v43
	v_mov_b32_dpp v42, v25 row_shl:1 row_mask:0xf bank_mask:0xf
	v_fma_f32 v42, v93, v42, v89
	v_fmac_f32_e32 v42, v73, v25
	v_fmac_f32_e32 v42, v69, v54
	v_mul_f32_e32 v41, v41, v43
	v_mul_f32_e32 v41, v42, v41
	v_mov_b32_dpp v49, v30 row_shr:1 row_mask:0xf bank_mask:0xf
	v_cndmask_b32_e64 v34, 0, v44, s[4:5]
	v_mov_b32_dpp v42, v22 row_ror:15 row_mask:0xf bank_mask:0xf
	v_cndmask_b32_e32 v53, 0, v38, vcc
	s_nop 0
	v_mov_b32_dpp v42, v30 row_shl:1 row_mask:0xf bank_mask:0xf
	v_fma_f32 v42, v86, v42, v66
	v_fmac_f32_e32 v42, v82, v30
	v_fmac_f32_e32 v42, v78, v49
	v_mul_f32_e32 v44, 0xbfb8aa3b, v42
	v_exp_f32_e32 v44, v44
	v_mov_b32_dpp v43, v18 row_ror:15 row_mask:0xf bank_mask:0xf
	v_mov_b32_dpp v53, v26 row_shr:1 row_mask:0xf bank_mask:0xf
	v_mov_b32_dpp v48, v31 row_shr:1 row_mask:0xf bank_mask:0xf
	v_add_f32_e32 v44, 1.0, v44
	v_rcp_f32_e32 v44, v44
	v_mov_b32_dpp v43, v26 row_shl:1 row_mask:0xf bank_mask:0xf
	v_fma_f32 v43, v94, v43, v90
	v_fmac_f32_e32 v43, v74, v26
	v_fmac_f32_e32 v43, v70, v53
	v_mul_f32_e32 v42, v42, v44
	v_mul_f32_e32 v42, v43, v42
	v_cndmask_b32_e64 v36, 0, v45, s[4:5]
	v_mov_b32_dpp v43, v23 row_ror:15 row_mask:0xf bank_mask:0xf
	v_mov_b32_dpp v52, v27 row_shr:1 row_mask:0xf bank_mask:0xf
	v_mov_b32_dpp v44, v19 row_ror:15 row_mask:0xf bank_mask:0xf
	v_mov_b32_dpp v43, v31 row_shl:1 row_mask:0xf bank_mask:0xf
	v_fma_f32 v43, v87, v43, v67
	v_fmac_f32_e32 v43, v83, v31
	v_fmac_f32_e32 v43, v79, v48
	v_mul_f32_e32 v45, 0xbfb8aa3b, v43
	v_exp_f32_e32 v45, v45
	v_mov_b32_dpp v44, v27 row_shl:1 row_mask:0xf bank_mask:0xf
	v_fma_f32 v44, v95, v44, v91
	v_fmac_f32_e32 v44, v75, v27
	v_add_f32_e32 v45, 1.0, v45
	v_rcp_f32_e32 v45, v45
	v_fmac_f32_e32 v44, v71, v52
	v_cvt_pk_bf16_f32 v40, v40, v41
	v_mov_b32_dpp v39, v6 row_shl:1 row_mask:0xf bank_mask:0xf
	v_mul_f32_e32 v43, v43, v45
	v_mul_f32_e32 v43, v44, v43
	v_cvt_pk_bf16_f32 v41, v42, v43
	flat_store_dwordx2 v[98:99], v[40:41] offset:8
	v_cndmask_b32_e64 v38, 0, v46, s[4:5]
	v_mov_b32_dpp v40, v28 row_ror:1 row_mask:0xf bank_mask:0xf
	v_mov_b32_dpp v41, v8 row_ror:15 row_mask:0xf bank_mask:0xf
	s_nop 0
	v_mov_b32_dpp v40, v20 row_shr:1 row_mask:0xf bank_mask:0xf
	v_mov_b32_dpp v28, v24 row_ror:1 row_mask:0xf bank_mask:0xf
	v_mov_b32_dpp v41, v16 row_shl:1 row_mask:0xf bank_mask:0xf
	v_fma_f32 v41, v92, v41, v88
	v_mov_b32_dpp v24, v12 row_ror:15 row_mask:0xf bank_mask:0xf
	v_mov_b32_dpp v28, v16 row_shr:1 row_mask:0xf bank_mask:0xf
	v_fmac_f32_e32 v41, v72, v16
	v_mov_b32_dpp v24, v20 row_shl:1 row_mask:0xf bank_mask:0xf
	v_fma_f32 v24, v84, v24, v64
	v_fmac_f32_e32 v24, v80, v20
	v_fmac_f32_e32 v24, v76, v40
	v_mul_f32_e32 v40, 0xbfb8aa3b, v24
	v_fmac_f32_e32 v41, v68, v28
	v_exp_f32_e32 v40, v40
	v_mov_b32_dpp v38, v2 row_shl:1 row_mask:0xf bank_mask:0xf
	v_mov_b32_dpp v28, v29 row_ror:1 row_mask:0xf bank_mask:0xf
	v_add_f32_e32 v40, 1.0, v40
	v_rcp_f32_e32 v40, v40
	v_mov_b32_dpp v29, v25 row_ror:1 row_mask:0xf bank_mask:0xf
	v_mov_b32_dpp v28, v21 row_shr:1 row_mask:0xf bank_mask:0xf
	v_mul_f32_e32 v24, v24, v40
	v_mov_b32_dpp v25, v13 row_ror:15 row_mask:0xf bank_mask:0xf
	v_mov_b32_dpp v29, v17 row_shr:1 row_mask:0xf bank_mask:0xf
	s_nop 0
	v_mov_b32_dpp v25, v21 row_shl:1 row_mask:0xf bank_mask:0xf
	v_fma_f32 v25, v85, v25, v65
	v_fmac_f32_e32 v25, v81, v21
	v_fmac_f32_e32 v25, v77, v28
	v_mul_f32_e32 v28, 0xbfb8aa3b, v25
	v_exp_f32_e32 v28, v28
	v_mov_b32_dpp v40, v9 row_ror:15 row_mask:0xf bank_mask:0xf
	v_mul_f32_e32 v24, v41, v24
	v_mov_b32_dpp v37, v5 row_shl:1 row_mask:0xf bank_mask:0xf
	v_mov_b32_dpp v40, v17 row_shl:1 row_mask:0xf bank_mask:0xf
	v_add_f32_e32 v28, 1.0, v28
	v_fma_f32 v40, v93, v40, v89
	v_rcp_f32_e32 v28, v28
	v_fmac_f32_e32 v40, v73, v17
	v_fmac_f32_e32 v40, v69, v29
	v_mul_f32_e32 v25, v25, v28
	v_mov_b32_dpp v29, v26 row_ror:1 row_mask:0xf bank_mask:0xf
	v_mov_b32_dpp v28, v30 row_ror:1 row_mask:0xf bank_mask:0xf
	v_mov_b32_dpp v26, v14 row_ror:15 row_mask:0xf bank_mask:0xf
	s_nop 0
	v_mov_b32_dpp v28, v22 row_shr:1 row_mask:0xf bank_mask:0xf
	v_mov_b32_dpp v30, v10 row_ror:15 row_mask:0xf bank_mask:0xf
	v_mov_b32_dpp v26, v22 row_shl:1 row_mask:0xf bank_mask:0xf
	v_fma_f32 v26, v86, v26, v66
	v_fmac_f32_e32 v26, v82, v22
	v_fmac_f32_e32 v26, v78, v28
	v_mul_f32_e32 v28, 0xbfb8aa3b, v26
	v_exp_f32_e32 v28, v28
	v_mov_b32_dpp v30, v18 row_shl:1 row_mask:0xf bank_mask:0xf
	v_fma_f32 v30, v94, v30, v90
	v_mov_b32_dpp v29, v18 row_shr:1 row_mask:0xf bank_mask:0xf
	v_add_f32_e32 v28, 1.0, v28
	v_rcp_f32_e32 v28, v28
	v_fmac_f32_e32 v30, v74, v18
	v_fmac_f32_e32 v30, v70, v29
	v_mul_f32_e32 v26, v26, v28
	v_mov_b32_dpp v29, v27 row_ror:1 row_mask:0xf bank_mask:0xf
	v_mov_b32_dpp v28, v31 row_ror:1 row_mask:0xf bank_mask:0xf
	v_mul_f32_e32 v26, v30, v26
	v_mov_b32_dpp v27, v15 row_ror:15 row_mask:0xf bank_mask:0xf
	v_mov_b32_dpp v28, v23 row_shr:1 row_mask:0xf bank_mask:0xf
	s_nop 0
	v_mov_b32_dpp v27, v23 row_shl:1 row_mask:0xf bank_mask:0xf
	v_fma_f32 v27, v87, v27, v67
	v_fmac_f32_e32 v27, v83, v23
	v_fmac_f32_e32 v27, v79, v28
	v_mul_f32_e32 v28, 0xbfb8aa3b, v27
	v_exp_f32_e32 v28, v28
	v_mov_b32_dpp v30, v11 row_ror:15 row_mask:0xf bank_mask:0xf
	v_mov_b32_dpp v29, v19 row_shr:1 row_mask:0xf bank_mask:0xf
	v_mul_f32_e32 v25, v40, v25
	v_add_f32_e32 v28, 1.0, v28
	v_rcp_f32_e32 v28, v28
	v_mov_b32_dpp v30, v19 row_shl:1 row_mask:0xf bank_mask:0xf
	v_fma_f32 v30, v95, v30, v91
	v_fmac_f32_e32 v30, v75, v19
	v_fmac_f32_e32 v30, v71, v29
	v_mul_f32_e32 v27, v27, v28
	v_cvt_pk_bf16_f32 v24, v24, v25
	v_mul_f32_e32 v27, v30, v27
	v_cvt_pk_bf16_f32 v25, v26, v27
	flat_store_dwordx2 v[100:101], v[24:25] offset:8
	v_mov_b32_dpp v36, v1 row_shl:1 row_mask:0xf bank_mask:0xf
	v_mov_b32_dpp v24, v20 row_ror:1 row_mask:0xf bank_mask:0xf
	v_mov_b32_dpp v25, v0 row_ror:15 row_mask:0xf bank_mask:0xf
	s_nop 0
	v_mov_b32_dpp v24, v12 row_shr:1 row_mask:0xf bank_mask:0xf
	v_mov_b32_dpp v20, v16 row_ror:1 row_mask:0xf bank_mask:0xf
	v_mov_b32_dpp v25, v8 row_shl:1 row_mask:0xf bank_mask:0xf
	v_fma_f32 v25, v92, v25, v88
	v_mov_b32_dpp v16, v4 row_ror:15 row_mask:0xf bank_mask:0xf
	v_mov_b32_dpp v20, v8 row_shr:1 row_mask:0xf bank_mask:0xf
	v_fmac_f32_e32 v25, v72, v8
	v_mov_b32_dpp v16, v12 row_shl:1 row_mask:0xf bank_mask:0xf
	v_fma_f32 v16, v84, v16, v64
	v_fmac_f32_e32 v16, v80, v12
	v_fmac_f32_e32 v16, v76, v24
	v_mul_f32_e32 v24, 0xbfb8aa3b, v16
	v_fmac_f32_e32 v25, v68, v20
	v_exp_f32_e32 v24, v24
	v_mov_b32_dpp v35, v4 row_shl:1 row_mask:0xf bank_mask:0xf
	v_mov_b32_dpp v20, v21 row_ror:1 row_mask:0xf bank_mask:0xf
	v_add_f32_e32 v24, 1.0, v24
	v_rcp_f32_e32 v24, v24
	v_mov_b32_dpp v21, v17 row_ror:1 row_mask:0xf bank_mask:0xf
	v_mov_b32_dpp v20, v13 row_shr:1 row_mask:0xf bank_mask:0xf
	v_mul_f32_e32 v16, v16, v24
	v_mov_b32_dpp v17, v5 row_ror:15 row_mask:0xf bank_mask:0xf
	v_mov_b32_dpp v21, v9 row_shr:1 row_mask:0xf bank_mask:0xf
	s_nop 0
	v_mov_b32_dpp v17, v13 row_shl:1 row_mask:0xf bank_mask:0xf
	v_fma_f32 v17, v85, v17, v65
	v_fmac_f32_e32 v17, v81, v13
	v_fmac_f32_e32 v17, v77, v20
	v_mul_f32_e32 v20, 0xbfb8aa3b, v17
	v_exp_f32_e32 v20, v20
	v_mov_b32_dpp v24, v1 row_ror:15 row_mask:0xf bank_mask:0xf
	v_mul_f32_e32 v16, v25, v16
	v_mov_b32_dpp v33, v7 row_shl:1 row_mask:0xf bank_mask:0xf
	v_mov_b32_dpp v24, v9 row_shl:1 row_mask:0xf bank_mask:0xf
	v_add_f32_e32 v20, 1.0, v20
	v_fma_f32 v24, v93, v24, v89
	v_rcp_f32_e32 v20, v20
	v_fmac_f32_e32 v24, v73, v9
	v_fmac_f32_e32 v24, v69, v21
	v_mul_f32_e32 v17, v17, v20
	v_mov_b32_dpp v21, v18 row_ror:1 row_mask:0xf bank_mask:0xf
	v_mov_b32_dpp v20, v22 row_ror:1 row_mask:0xf bank_mask:0xf
	v_mov_b32_dpp v18, v6 row_ror:15 row_mask:0xf bank_mask:0xf
	s_nop 0
	v_mov_b32_dpp v20, v14 row_shr:1 row_mask:0xf bank_mask:0xf
	v_mov_b32_dpp v22, v2 row_ror:15 row_mask:0xf bank_mask:0xf
	v_mov_b32_dpp v18, v14 row_shl:1 row_mask:0xf bank_mask:0xf
	v_fma_f32 v18, v86, v18, v66
	v_fmac_f32_e32 v18, v82, v14
	v_fmac_f32_e32 v18, v78, v20
	v_mul_f32_e32 v20, 0xbfb8aa3b, v18
	v_exp_f32_e32 v20, v20
	v_mov_b32_dpp v22, v10 row_shl:1 row_mask:0xf bank_mask:0xf
	v_fma_f32 v22, v94, v22, v90
	v_mov_b32_dpp v21, v10 row_shr:1 row_mask:0xf bank_mask:0xf
	v_add_f32_e32 v20, 1.0, v20
	v_rcp_f32_e32 v20, v20
	v_fmac_f32_e32 v22, v74, v10
	v_fmac_f32_e32 v22, v70, v21
	v_mul_f32_e32 v18, v18, v20
	v_mov_b32_dpp v21, v19 row_ror:1 row_mask:0xf bank_mask:0xf
	v_mov_b32_dpp v20, v23 row_ror:1 row_mask:0xf bank_mask:0xf
	v_mul_f32_e32 v18, v22, v18
	v_mov_b32_dpp v19, v7 row_ror:15 row_mask:0xf bank_mask:0xf
	v_mov_b32_dpp v20, v15 row_shr:1 row_mask:0xf bank_mask:0xf
	s_nop 0
	v_mov_b32_dpp v19, v15 row_shl:1 row_mask:0xf bank_mask:0xf
	v_fma_f32 v19, v87, v19, v67
	v_fmac_f32_e32 v19, v83, v15
	v_fmac_f32_e32 v19, v79, v20
	v_mul_f32_e32 v20, 0xbfb8aa3b, v19
	v_exp_f32_e32 v20, v20
	v_mov_b32_dpp v22, v3 row_ror:15 row_mask:0xf bank_mask:0xf
	v_mov_b32_dpp v21, v11 row_shr:1 row_mask:0xf bank_mask:0xf
	v_mul_f32_e32 v17, v24, v17
	v_add_f32_e32 v20, 1.0, v20
	v_rcp_f32_e32 v20, v20
	v_mov_b32_dpp v22, v11 row_shl:1 row_mask:0xf bank_mask:0xf
	v_fma_f32 v22, v95, v22, v91
	v_fmac_f32_e32 v22, v75, v11
	v_fmac_f32_e32 v22, v71, v21
	v_mul_f32_e32 v19, v19, v20
	v_cvt_pk_bf16_f32 v16, v16, v17
	v_mul_f32_e32 v19, v22, v19
	v_cvt_pk_bf16_f32 v17, v18, v19
	flat_store_dwordx2 v[102:103], v[16:17] offset:8
	v_fma_f32 v17, v86, v39, v66
	v_fmac_f32_e32 v17, v82, v6
	v_mov_b32_dpp v16, v12 row_ror:1 row_mask:0xf bank_mask:0xf
	v_fmac_f32_e32 v67, v87, v33
	s_nop 0
	v_mov_b32_dpp v16, v4 row_shr:1 row_mask:0xf bank_mask:0xf
	v_mov_b32_dpp v12, v8 row_ror:1 row_mask:0xf bank_mask:0xf
	v_mov_b32_dpp v34, v0 row_shl:1 row_mask:0xf bank_mask:0xf
	v_fmac_f32_e32 v67, v83, v7
	v_mov_b32_dpp v8, v13 row_ror:1 row_mask:0xf bank_mask:0xf
	v_mov_b32_dpp v12, v0 row_shr:1 row_mask:0xf bank_mask:0xf
	s_nop 0
	v_mov_b32_dpp v8, v5 row_shr:1 row_mask:0xf bank_mask:0xf
	v_mov_b32_dpp v13, v9 row_ror:1 row_mask:0xf bank_mask:0xf
	v_cndmask_b32_e64 v32, 0, v47, s[4:5]
	s_nop 0
	v_mov_b32_dpp v13, v1 row_shr:1 row_mask:0xf bank_mask:0xf
	v_mov_b32_dpp v9, v14 row_ror:1 row_mask:0xf bank_mask:0xf
	v_mov_b32_dpp v32, v3 row_shl:1 row_mask:0xf bank_mask:0xf
	s_nop 0
	v_mov_b32_dpp v9, v6 row_shr:1 row_mask:0xf bank_mask:0xf
	v_fmac_f32_e32 v17, v78, v9
	v_mul_f32_e32 v6, 0xbfb8aa3b, v17
	v_exp_f32_e32 v6, v6
	v_mov_b32_dpp v14, v10 row_ror:1 row_mask:0xf bank_mask:0xf
	v_add_f32_e32 v6, 1.0, v6
	v_rcp_f32_e32 v6, v6
	v_mov_b32_dpp v9, v11 row_ror:1 row_mask:0xf bank_mask:0xf
	v_fma_f32 v11, v94, v38, v90
	v_mov_b32_dpp v14, v2 row_shr:1 row_mask:0xf bank_mask:0xf
	v_fmac_f32_e32 v11, v74, v2
	v_mul_f32_e32 v2, v17, v6
	v_fma_f32 v6, v85, v37, v65
	v_fmac_f32_e32 v6, v81, v5
	v_fmac_f32_e32 v6, v77, v8
	v_mul_f32_e32 v5, 0xbfb8aa3b, v6
	v_exp_f32_e32 v5, v5
	v_fma_f32 v8, v93, v36, v89
	v_fmac_f32_e32 v8, v73, v1
	v_mov_b32_dpp v10, v15 row_ror:1 row_mask:0xf bank_mask:0xf
	v_add_f32_e32 v1, 1.0, v5
	v_fma_f32 v5, v84, v35, v64
	v_fmac_f32_e32 v5, v80, v4
	v_fmac_f32_e32 v5, v76, v16
	v_mul_f32_e32 v4, 0xbfb8aa3b, v5
	v_exp_f32_e32 v4, v4
	v_rcp_f32_e32 v1, v1
	v_mov_b32_dpp v10, v7 row_shr:1 row_mask:0xf bank_mask:0xf
	v_fmac_f32_e32 v67, v79, v10
	v_add_f32_e32 v4, 1.0, v4
	v_rcp_f32_e32 v4, v4
	v_mul_f32_e32 v1, v6, v1
	v_fma_f32 v6, v92, v34, v88
	v_fmac_f32_e32 v6, v72, v0
	v_mul_f32_e32 v0, v5, v4
	v_mul_f32_e32 v4, 0xbfb8aa3b, v67
	v_exp_f32_e32 v4, v4
	v_fmac_f32_e32 v91, v95, v32
	v_fmac_f32_e32 v8, v69, v13
	v_fmac_f32_e32 v6, v68, v12
	v_add_f32_e32 v4, 1.0, v4
	v_rcp_f32_e32 v4, v4
	v_mov_b32_dpp v9, v3 row_shr:1 row_mask:0xf bank_mask:0xf
	v_fmac_f32_e32 v91, v75, v3
	v_fmac_f32_e32 v11, v70, v14
	v_mul_f32_e32 v1, v8, v1
	v_mul_f32_e32 v0, v6, v0
	v_fmac_f32_e32 v91, v71, v9
	v_mul_f32_e32 v3, v67, v4
	v_mul_f32_e32 v2, v11, v2
	v_mul_f32_e32 v3, v91, v3
	v_cvt_pk_bf16_f32 v0, v0, v1
	v_cvt_pk_bf16_f32 v1, v2, v3
	flat_store_dwordx2 v[104:105], v[0:1] offset:8
	s_andn2_b64 vcc, exec, s[82:83]
	s_mov_b64 s[4:5], -1
	s_cbranch_vccnz .LBB0_43
	s_andn2_b64 vcc, exec, s[88:89]
	s_cbranch_vccnz .LBB0_42
	s_barrier
	s_branch .LBB0_42
